# v7
# speedup vs baseline: 1.0120x; 1.0028x over previous
; __device__ __forceinline__ unsigned pack2(float a, float b) { const f32v2_ v = {a, b}; const bf16v2_ r = __builtin_convertvector(v, bf16v2_); return __builtin_bit_cast(unsigned, r); }
; #define SB_ __builtin_amdgcn_sched_barrier(0)
; __device__ __forceinline__ void scan_phase(const Params& p, char* shmc, int tid, int wv) {
;     ...
;       float4 dd[4];
; #pragma unroll
;       for (int m = 0; m < 4; ++m) dd[m] = *(const float4*)(B + OFF_DD + (16 * m + 4 * quad) * 4);
;       SB_;
;       bf16x8 Vb[2];
; #pragma unroll
;       for (int kk = 0; kk < 2; ++kk) {
;         const u32x4 w = {pack2(Vn[2 * kk][0], Vn[2 * kk][1]), pack2(Vn[2 * kk][2], Vn[2 * kk][3]),
;                          pack2(Vn[2 * kk + 1][0], Vn[2 * kk + 1][1]), pack2(Vn[2 * kk + 1][2], Vn[2 * kk + 1][3])};
;         Vb[kk] = __builtin_bit_cast(bf16x8, w);
;         *(bf16x8*)(xv + kk * 1024 + lane * 16) = Vb[kk];
;       }
;       asm volatile("s_waitcnt lgkmcnt(0)" ::: "memory");
;       if (lane == 0) *vfl = (unsigned)(n + 1);
;       SB_;
; #pragma unroll
;       for (int m = 0; m < 4; ++m) {
;         f32x4 s_ = S[m];
;         s_[0] *= dd[m].x; s_[1] *= dd[m].y; s_[2] *= dd[m].z; s_[3] *= dd[m].w;
;         s_ = __builtin_amdgcn_mfma_f32_16x16x32_bf16(fc[2 * m], Vb[0], s_, 0, 0, 0);
;         S[m] = __builtin_amdgcn_mfma_f32_16x16x32_bf16(fc[2 * m + 1], Vb[1], s_, 0, 0, 0);
;       }
; #pragma unroll
;       for (int m = 0; m < 4; ++m) dd[m] = *(const float4*)(B + OFF_DD + (16 * (4 + m) + 4 * quad) * 4);
; #pragma unroll
;       for (int m = 0; m < 4; ++m) {
;         f32x4 s_ = S[4 + m];
;         s_[0] *= dd[m].x; s_[1] *= dd[m].y; s_[2] *= dd[m].z; s_[3] *= dd[m].w;
;         s_ = __builtin_amdgcn_mfma_f32_16x16x32_bf16(fd[2 * m], Vb[0], s_, 0, 0, 0);
;         S[4 + m] = __builtin_amdgcn_mfma_f32_16x16x32_bf16(fd[2 * m + 1], Vb[1], s_, 0, 0, 0);
;       }
; #pragma unroll
;       for (int kk = 0; kk < 4; ++kk) {
;         const u32x4 w = {pack2(S[2 * kk][0], S[2 * kk][1]), pack2(S[2 * kk][2], S[2 * kk][3]),
;                          pack2(S[2 * kk + 1][0], S[2 * kk + 1][1]), pack2(S[2 * kk + 1][2], S[2 * kk + 1][3])};
;         Sb[kk] = __builtin_bit_cast(bf16x8, w);
;       }
;       while (*sfl < (unsigned)(n + 1)) { }
.LBB0_385:
	s_nop 4
	v_cvt_pk_bf16_f32 v100, v184, v185
	v_cvt_pk_bf16_f32 v101, v186, v187
	v_cvt_pk_bf16_f32 v102, v192, v193
	v_cvt_pk_bf16_f32 v103, v194, v195
	v_add_u32_e32 v225, 0x20c00, v0
	v_cvt_pk_bf16_f32 v104, v180, v181
	v_cvt_pk_bf16_f32 v105, v182, v183
	v_cvt_pk_bf16_f32 v106, v188, v189
	v_cvt_pk_bf16_f32 v107, v190, v191
	ds_write_b128 v225, v[100:103]
	ds_write_b128 v225, v[104:107] offset:1024
	s_waitcnt lgkmcnt(0)
	s_and_saveexec_b64 s[16:17], s[10:11]
	s_cbranch_execz .LBB0_387
	s_or_b32 s15, s7, 1
	v_mov_b32_e32 v180, s33
	v_mov_b32_e32 v182, s15
	ds_write_b32 v180, v182
.LBB0_387:
	s_or_b64 exec, exec, s[16:17]
	ds_read_b128 v[200:203], v206 offset:62464
	ds_read_b128 v[196:199], v206 offset:62528
	ds_read_b128 v[112:115], v206 offset:62592
	ds_read_b128 v[108:111], v206 offset:62656
	s_waitcnt lgkmcnt(0)
	v_pk_mul_f32 v[78:79], v[78:79], v[114:115]
	v_pk_mul_f32 v[76:77], v[76:77], v[112:113]
	v_pk_mul_f32 v[90:91], v[90:91], v[110:111]
	v_pk_mul_f32 v[88:89], v[88:89], v[108:109]
	ds_read_b128 v[108:111], v206 offset:62720
	ds_read_b128 v[112:115], v206 offset:62784
	v_pk_mul_f32 v[70:71], v[70:71], v[202:203]
	v_pk_mul_f32 v[68:69], v[68:69], v[200:201]
	v_pk_mul_f32 v[74:75], v[74:75], v[198:199]
	s_waitcnt lgkmcnt(1)
	v_pk_mul_f32 v[82:83], v[82:83], v[110:111]
	v_pk_mul_f32 v[80:81], v[80:81], v[108:109]
	s_waitcnt lgkmcnt(0)
	v_pk_mul_f32 v[94:95], v[94:95], v[114:115]
	v_pk_mul_f32 v[92:93], v[92:93], v[112:113]
	ds_read_b128 v[108:111], v206 offset:62848
	ds_read_b128 v[112:115], v206 offset:62912
	v_pk_mul_f32 v[72:73], v[72:73], v[196:197]
	v_mfma_f32_16x16x32_bf16 v[68:71], v[172:175], v[100:103], v[68:71]
	s_mov_b64 s[16:17], 0
	s_waitcnt lgkmcnt(1)
	v_pk_mul_f32 v[86:87], v[86:87], v[110:111]
	v_pk_mul_f32 v[84:85], v[84:85], v[108:109]
	s_waitcnt lgkmcnt(0)
	s_add_i32 s15, s35, 0x110
	v_mov_b32_e32 v228, s15
	ds_read_b32 v227, v228
	v_pk_mul_f32 v[98:99], v[98:99], v[114:115]
	v_pk_mul_f32 v[96:97], v[96:97], v[112:113]
	v_mfma_f32_16x16x32_bf16 v[72:75], v[164:167], v[100:103], v[72:75]
	v_mfma_f32_16x16x32_bf16 v[76:79], v[156:159], v[100:103], v[76:79]
	v_mfma_f32_16x16x32_bf16 v[88:91], v[152:155], v[100:103], v[88:91]
	v_mfma_f32_16x16x32_bf16 v[80:83], v[140:143], v[100:103], v[80:83]
	v_mfma_f32_16x16x32_bf16 v[92:95], v[136:139], v[100:103], v[92:95]
	v_mfma_f32_16x16x32_bf16 v[84:87], v[124:127], v[100:103], v[84:87]
	v_mfma_f32_16x16x32_bf16 v[96:99], v[120:123], v[100:103], v[96:99]
	v_mfma_f32_16x16x32_bf16 v[68:71], v[176:179], v[104:107], v[68:71]
	v_mfma_f32_16x16x32_bf16 v[72:75], v[168:171], v[104:107], v[72:75]
	v_mfma_f32_16x16x32_bf16 v[76:79], v[160:163], v[104:107], v[76:79]
	v_mfma_f32_16x16x32_bf16 v[88:91], v[148:151], v[104:107], v[88:91]
	v_mfma_f32_16x16x32_bf16 v[80:83], v[144:147], v[104:107], v[80:83]
	v_mfma_f32_16x16x32_bf16 v[92:95], v[132:135], v[104:107], v[92:95]
	v_mfma_f32_16x16x32_bf16 v[84:87], v[128:131], v[104:107], v[84:87]
	v_mfma_f32_16x16x32_bf16 v[96:99], v[116:119], v[104:107], v[96:99]
	s_waitcnt lgkmcnt(0)
	v_cmp_lt_u32_e32 vcc, s7, v227
	s_cbranch_vccnz .Lrec_f1

; __device__ __forceinline__ unsigned pack2(float a, float b) { const f32v2_ v = {a, b}; const bf16v2_ r = __builtin_convertvector(v, bf16v2_); return __builtin_bit_cast(unsigned, r); }
; #define SB_ __builtin_amdgcn_sched_barrier(0)
; #define LD272(dst, OFF, g) _Pragma("unroll") for (int f = 0; f < 8; ++f) dst[f] = *(const bf16x8*)(b272 + (OFF) + (16 * (2 * (g) + (f >> 2))) * 272 + (f & 3) * 64)
; #define LDK(dst, g) _Pragma("unroll") for (int f = 0; f < 8; ++f) dst[f] = *(const bf16x8*)(b144 + OFF_KD + (16 * (4 * (g) + (f >> 1))) * 144 + (f & 1) * 64)
; __device__ __forceinline__ void scan_phase(const Params& p, char* shmc, int tid, int wv) {
;     ...
;       const char* B = shmc + par * BUF;
;       const char* b272 = B + r * 272 + quad * 16;
;       const char* b144 = B + r * 144 + quad * 16;
;       bf16x8 fa[8], fb[8], fc[8], fd[8];
;       if (type) { LD272(fa, OFF_WN, 0); LD272(fb, OFF_WN, 1); }
;       LDK(fc, 0); LDK(fd, 1); SB_;
;     ...
; #pragma unroll
;       for (int kk = 0; kk < 4; ++kk) {
;         const u32x4 w = {pack2(S[2 * kk][0], S[2 * kk][1]), pack2(S[2 * kk][2], S[2 * kk][3]),
;                          pack2(S[2 * kk + 1][0], S[2 * kk + 1][1]), pack2(S[2 * kk + 1][2], S[2 * kk + 1][3])};
;         Sb[kk] = __builtin_bit_cast(bf16x8, w);
;       }
;       while (*sfl < (unsigned)(n + 1)) { }
; #pragma unroll
;       for (int kk = 0; kk < 4; ++kk) *(bf16x8*)(xs + kk * 1024 + lane * 16) = Sb[kk];
;     }
;     asm volatile("s_waitcnt lgkmcnt(0)" ::: "memory");
;     __builtin_amdgcn_s_barrier();
.Lrec_f1:
	v_cvt_pk_bf16_f32 v164, v68, v69
	v_cvt_pk_bf16_f32 v165, v70, v71
	v_cvt_pk_bf16_f32 v166, v72, v73
	v_cvt_pk_bf16_f32 v167, v74, v75
	v_cvt_pk_bf16_f32 v168, v76, v77
	v_cvt_pk_bf16_f32 v169, v78, v79
	v_cvt_pk_bf16_f32 v170, v88, v89
	v_cvt_pk_bf16_f32 v171, v90, v91
	v_cvt_pk_bf16_f32 v172, v80, v81
	v_cvt_pk_bf16_f32 v173, v82, v83
	v_cvt_pk_bf16_f32 v174, v92, v93
	v_cvt_pk_bf16_f32 v175, v94, v95
	v_cvt_pk_bf16_f32 v176, v84, v85
	v_cvt_pk_bf16_f32 v177, v86, v87
	v_cvt_pk_bf16_f32 v178, v96, v97
	v_cvt_pk_bf16_f32 v179, v98, v99
	ds_write_b128 v1, v[164:167]
	ds_write_b128 v1, v[168:171] offset:1024
	ds_write_b128 v1, v[172:175] offset:2048
	ds_write_b128 v1, v[176:179] offset:3072
	s_waitcnt lgkmcnt(0)
	s_and_b64 vcc, exec, s[8:9]
	s_barrier
	s_cbranch_vccnz .LBB0_391
	ds_read_b128 v[4:7], v209 offset:62976
	ds_read_b128 v[8:11], v209 offset:63040
	ds_read_b128 v[12:15], v209 offset:63104
	ds_read_b128 v[16:19], v209 offset:63168
	ds_read_b128 v[20:23], v210 offset:4352
	ds_read_b128 v[24:27], v210 offset:4416
	ds_read_b128 v[28:31], v210 offset:4480
	ds_read_b128 v[32:35], v210 offset:4544
	ds_read_b128 v[36:39], v210 offset:8704
	ds_read_b128 v[40:43], v210 offset:8768
	ds_read_b128 v[44:47], v210 offset:8832
	ds_read_b128 v[48:51], v210 offset:8896
	ds_read_b128 v[52:55], v210 offset:13056
	ds_read_b128 v[56:59], v210 offset:13120
	ds_read_b128 v[60:63], v210 offset:13184
	ds_read_b128 v[64:67], v210 offset:13248

; __device__ __forceinline__ unsigned pack2(float a, float b) { const f32v2_ v = {a, b}; const bf16v2_ r = __builtin_convertvector(v, bf16v2_); return __builtin_bit_cast(unsigned, r); }
; #define SB_ __builtin_amdgcn_sched_barrier(0)
; __device__ __forceinline__ void scan_phase(const Params& p, char* shmc, int tid, int wv) {
;     ...
;       float4 dd[4];
; #pragma unroll
;       for (int m = 0; m < 4; ++m) dd[m] = *(const float4*)(B + OFF_DD + (16 * m + 4 * quad) * 4);
;       SB_;
;       bf16x8 Vb[2];
; #pragma unroll
;       for (int kk = 0; kk < 2; ++kk) {
;         const u32x4 w = {pack2(Vn[2 * kk][0], Vn[2 * kk][1]), pack2(Vn[2 * kk][2], Vn[2 * kk][3]),
;                          pack2(Vn[2 * kk + 1][0], Vn[2 * kk + 1][1]), pack2(Vn[2 * kk + 1][2], Vn[2 * kk + 1][3])};
;         Vb[kk] = __builtin_bit_cast(bf16x8, w);
;         *(bf16x8*)(xv + kk * 1024 + lane * 16) = Vb[kk];
;       }
;       asm volatile("s_waitcnt lgkmcnt(0)" ::: "memory");
;       if (lane == 0) *vfl = (unsigned)(n + 1);
;       SB_;
; #pragma unroll
;       for (int m = 0; m < 4; ++m) {
;         f32x4 s_ = S[m];
;         s_[0] *= dd[m].x; s_[1] *= dd[m].y; s_[2] *= dd[m].z; s_[3] *= dd[m].w;
;         s_ = __builtin_amdgcn_mfma_f32_16x16x32_bf16(fc[2 * m], Vb[0], s_, 0, 0, 0);
;         S[m] = __builtin_amdgcn_mfma_f32_16x16x32_bf16(fc[2 * m + 1], Vb[1], s_, 0, 0, 0);
;       }
; #pragma unroll
;       for (int m = 0; m < 4; ++m) dd[m] = *(const float4*)(B + OFF_DD + (16 * (4 + m) + 4 * quad) * 4);
; #pragma unroll
;       for (int m = 0; m < 4; ++m) {
;         f32x4 s_ = S[4 + m];
;         s_[0] *= dd[m].x; s_[1] *= dd[m].y; s_[2] *= dd[m].z; s_[3] *= dd[m].w;
;         s_ = __builtin_amdgcn_mfma_f32_16x16x32_bf16(fd[2 * m], Vb[0], s_, 0, 0, 0);
;         S[4 + m] = __builtin_amdgcn_mfma_f32_16x16x32_bf16(fd[2 * m + 1], Vb[1], s_, 0, 0, 0);
;       }
; #pragma unroll
;       for (int kk = 0; kk < 4; ++kk) {
;         const u32x4 w = {pack2(S[2 * kk][0], S[2 * kk][1]), pack2(S[2 * kk][2], S[2 * kk][3]),
;                          pack2(S[2 * kk + 1][0], S[2 * kk + 1][1]), pack2(S[2 * kk + 1][2], S[2 * kk + 1][3])};
;         Sb[kk] = __builtin_bit_cast(bf16x8, w);
;       }
;       while (*sfl < (unsigned)(n + 1)) { }
.LBB0_393:
	s_nop 7
	v_cvt_pk_bf16_f32 v164, v180, v181
	v_cvt_pk_bf16_f32 v165, v182, v183
	v_cvt_pk_bf16_f32 v166, v192, v193
	v_cvt_pk_bf16_f32 v167, v194, v195
	v_cvt_pk_bf16_f32 v168, v184, v185
	v_cvt_pk_bf16_f32 v169, v186, v187
	v_cvt_pk_bf16_f32 v170, v188, v189
	v_cvt_pk_bf16_f32 v171, v190, v191
	ds_write_b128 v225, v[164:167]
	ds_write_b128 v225, v[168:171] offset:1024
	s_waitcnt lgkmcnt(0)
	s_and_saveexec_b64 s[16:17], s[10:11]
	s_cbranch_execz .LBB0_395
	s_add_i32 s18, s7, 2
	v_mov_b32_e32 v180, s33
	v_mov_b32_e32 v182, s18
	ds_write_b32 v180, v182
.LBB0_395:
	s_or_b64 exec, exec, s[16:17]
	v_add_u32_e32 v226, 0x1ea00, v206
	ds_read_b128 v[200:203], v226
	ds_read_b128 v[196:199], v226 offset:64
	ds_read_b128 v[176:179], v226 offset:128
	ds_read_b128 v[172:175], v226 offset:192
	s_or_b32 s18, s7, 1
	s_waitcnt lgkmcnt(0)
	v_pk_mul_f32 v[90:91], v[90:91], v[174:175]
	v_pk_mul_f32 v[88:89], v[88:89], v[172:173]
	v_pk_mul_f32 v[70:71], v[70:71], v[202:203]
	v_pk_mul_f32 v[68:69], v[68:69], v[200:201]
	v_mfma_f32_16x16x32_bf16 v[88:91], v[136:139], v[164:167], v[88:91]
	ds_read_b128 v[136:139], v211 offset:62720
	v_pk_mul_f32 v[74:75], v[74:75], v[198:199]
	v_pk_mul_f32 v[72:73], v[72:73], v[196:197]
	v_mfma_f32_16x16x32_bf16 v[88:91], v[132:135], v[168:171], v[88:91]
	ds_read_b128 v[132:135], v211 offset:62784
	v_pk_mul_f32 v[78:79], v[78:79], v[178:179]
	v_pk_mul_f32 v[76:77], v[76:77], v[176:177]
	s_waitcnt lgkmcnt(1)
	v_pk_mul_f32 v[82:83], v[82:83], v[138:139]
	v_pk_mul_f32 v[80:81], v[80:81], v[136:137]
	s_waitcnt lgkmcnt(0)
	v_pk_mul_f32 v[94:95], v[94:95], v[134:135]
	v_pk_mul_f32 v[92:93], v[92:93], v[132:133]
	v_mfma_f32_16x16x32_bf16 v[68:71], v[156:159], v[164:167], v[68:71]
	s_mov_b64 s[16:17], 0
	v_mfma_f32_16x16x32_bf16 v[92:95], v[120:123], v[164:167], v[92:95]
	ds_read_b128 v[120:123], v211 offset:62848
	v_mfma_f32_16x16x32_bf16 v[92:95], v[116:119], v[168:171], v[92:95]
	ds_read_b128 v[116:119], v211 offset:62912
	s_waitcnt lgkmcnt(1)
	v_pk_mul_f32 v[86:87], v[86:87], v[122:123]
	v_pk_mul_f32 v[84:85], v[84:85], v[120:121]
	v_mfma_f32_16x16x32_bf16 v[72:75], v[148:151], v[164:167], v[72:75]
	s_waitcnt lgkmcnt(0)
	s_add_i32 s15, s35, 0x110
	v_mov_b32_e32 v228, s15
	ds_read_b32 v227, v228
	v_pk_mul_f32 v[98:99], v[98:99], v[118:119]
	v_pk_mul_f32 v[96:97], v[96:97], v[116:117]
	v_mfma_f32_16x16x32_bf16 v[76:79], v[140:143], v[164:167], v[76:79]
	v_mfma_f32_16x16x32_bf16 v[80:83], v[124:127], v[164:167], v[80:83]
	v_mfma_f32_16x16x32_bf16 v[84:87], v[108:111], v[164:167], v[84:87]
	v_mfma_f32_16x16x32_bf16 v[96:99], v[104:107], v[164:167], v[96:99]
	v_mfma_f32_16x16x32_bf16 v[68:71], v[160:163], v[168:171], v[68:71]
	v_mfma_f32_16x16x32_bf16 v[72:75], v[152:155], v[168:171], v[72:75]
	v_mfma_f32_16x16x32_bf16 v[76:79], v[144:147], v[168:171], v[76:79]
	v_mfma_f32_16x16x32_bf16 v[80:83], v[128:131], v[168:171], v[80:83]
	v_mfma_f32_16x16x32_bf16 v[84:87], v[112:115], v[168:171], v[84:87]
	v_mfma_f32_16x16x32_bf16 v[96:99], v[100:103], v[168:171], v[96:99]
	s_waitcnt lgkmcnt(0)
	v_cmp_lt_u32_e32 vcc, s18, v227
	s_cbranch_vccnz .Lrec_f2

; __device__ __forceinline__ unsigned pack2(float a, float b) { const f32v2_ v = {a, b}; const bf16v2_ r = __builtin_convertvector(v, bf16v2_); return __builtin_bit_cast(unsigned, r); }
; __device__ __forceinline__ void scan_phase(const Params& p, char* shmc, int tid, int wv) {
;     ...
; #pragma unroll
;       for (int kk = 0; kk < 4; ++kk) {
;         const u32x4 w = {pack2(S[2 * kk][0], S[2 * kk][1]), pack2(S[2 * kk][2], S[2 * kk][3]),
;                          pack2(S[2 * kk + 1][0], S[2 * kk + 1][1]), pack2(S[2 * kk + 1][2], S[2 * kk + 1][3])};
;         Sb[kk] = __builtin_bit_cast(bf16x8, w);
;       }
;       while (*sfl < (unsigned)(n + 1)) { }
; #pragma unroll
;       for (int kk = 0; kk < 4; ++kk) *(bf16x8*)(xs + kk * 1024 + lane * 16) = Sb[kk];
;     }
;     asm volatile("s_waitcnt lgkmcnt(0)" ::: "memory");
;     __builtin_amdgcn_s_barrier();
;    }
;   }
.Lrec_f2:
	v_cvt_pk_bf16_f32 v100, v68, v69
	v_cvt_pk_bf16_f32 v101, v70, v71
	v_cvt_pk_bf16_f32 v102, v72, v73
	v_cvt_pk_bf16_f32 v103, v74, v75
	v_cvt_pk_bf16_f32 v104, v76, v77
	v_cvt_pk_bf16_f32 v105, v78, v79
	v_cvt_pk_bf16_f32 v106, v88, v89
	v_cvt_pk_bf16_f32 v107, v90, v91
	v_cvt_pk_bf16_f32 v108, v80, v81
	v_cvt_pk_bf16_f32 v109, v82, v83
	v_cvt_pk_bf16_f32 v110, v92, v93
	v_cvt_pk_bf16_f32 v111, v94, v95
	v_cvt_pk_bf16_f32 v112, v84, v85
	v_cvt_pk_bf16_f32 v113, v86, v87
	v_cvt_pk_bf16_f32 v114, v96, v97
	v_cvt_pk_bf16_f32 v115, v98, v99
	ds_write_b128 v1, v[100:103]
	ds_write_b128 v1, v[104:107] offset:1024
	ds_write_b128 v1, v[108:111] offset:2048
	ds_write_b128 v1, v[112:115] offset:3072
	s_waitcnt lgkmcnt(0)
	s_add_i32 s15, s7, 2
	s_cmpk_lt_u32 s7, 0xfe
	s_mov_b32 s7, s15
	s_barrier
	s_cbranch_scc1 .LBB0_381

; __device__ __forceinline__ float bflo(unsigned w) { return __uint_as_float(w << 16); }
; __device__ __forceinline__ float bfhi(unsigned w) { return __uint_as_float(w & 0xffff0000u); }
; __device__ __forceinline__ uint4 ldg16(const void* p) { const u32x4 v = *(const __attribute__((address_space(1))) u32x4*)(p); return make_uint4(v.x, v.y, v.z, v.w); }
; __device__ __forceinline__ void prepB(const Params& p, int h, int n, char* shmc, int tid, int wv) {
;     ...
;       for (int rr = 0; rr < 5; ++rr) {
;         const long tok = rowbase + t0 - 3 + rr;
;         rawv[rr] = make_uint4(0u, 0u, 0u, 0u);
;         if (tok >= 0) rawv[rr] = ldg16(GQKV + tok * 3072 + colg);
;       }
;       float w[4][8];
; #pragma unroll
;       for (int j = 0; j < 4; ++j) {
;         const float4 wa = *(const float4*)(p.a_conv_w + j * 3072 + colg), wb = *(const float4*)(p.a_conv_w + j * 3072 + colg + 4);
;         w[j][0] = wa.x; w[j][1] = wa.y; w[j][2] = wa.z; w[j][3] = wa.w; w[j][4] = wb.x; w[j][5] = wb.y; w[j][6] = wb.z; w[j][7] = wb.w;
;       }
;       float out[2][8];
; #pragma unroll
;       for (int tt = 0; tt < 2; ++tt)
; #pragma unroll
;         for (int i = 0; i < 8; ++i) out[tt][i] = 0.f;
; #pragma unroll
;       for (int rr = 0; rr < 5; ++rr) {
;         const uint4 raw = rawv[rr];
;         const unsigned rw[4] = {raw.x, raw.y, raw.z, raw.w};
;         float xv[8];
; #pragma unroll
;         for (int i = 0; i < 4; ++i) { xv[2 * i] = bflo(rw[i]); xv[2 * i + 1] = bfhi(rw[i]); }
.LBB0_440:
	s_or_b64 exec, exec, s[80:81]
	v_lshl_add_u64 v[96:97], v[34:35], 0, 2
	v_cmp_lt_i64_e64 s[80:81], -3, v[34:35]
	v_mov_b32_e32 v10, 0
	v_mov_b32_e32 v14, 0
	v_mov_b32_e32 v1, 0
	v_mov_b32_e32 v15, 0
	v_mov_b32_e32 v24, 0
	v_mov_b32_e32 v16, 0
	v_mov_b32_e32 v25, 0
	v_mov_b32_e32 v17, 0
	v_mov_b32_e32 v26, 0
	s_and_saveexec_b64 s[82:83], s[80:81]
	s_cbranch_execz .LBB0_442
	v_mad_u64_u32 v[0:1], s[8:9], v96, s42, v[22:23]
	v_mad_i32_i24 v1, v97, s42, v1
	global_load_dwordx4 v[14:17], v[0:1], off
.LBB0_442:
	s_or_b64 exec, exec, s[82:83]
	v_lshl_add_u64 v[98:99], s[14:15], 0, v[42:43]
	v_cmp_lt_i64_e64 s[82:83], -1, v[98:99]
	v_mov_b32_e32 v27, 0
	v_mov_b32_e32 v11, 0
	v_mov_b32_e32 v29, 0
	v_mov_b32_e32 v12, 0
	v_mov_b32_e32 v28, 0
	v_mov_b32_e32 v13, 0
	v_mov_b32_e32 v30, 0
	s_and_saveexec_b64 s[14:15], s[82:83]
	s_cbranch_execz .LBB0_444
	v_mad_u64_u32 v[10:11], s[8:9], v98, s42, v[22:23]
	v_mad_i32_i24 v11, v99, s42, v11
	global_load_dwordx4 v[10:13], v[10:11], off
.LBB0_444:
	s_or_b64 exec, exec, s[14:15]
	v_lshl_add_u64 v[100:101], v[34:35], 0, 4
	v_cmp_lt_i64_e64 s[84:85], -5, v[34:35]
	v_mov_b32_e32 v0, 0
	v_mov_b32_e32 v18, 0
	v_mov_b32_e32 v31, 0
	v_mov_b32_e32 v19, 0
	v_mov_b32_e32 v32, 0
	v_mov_b32_e32 v20, 0
	v_mov_b32_e32 v33, 0
	v_mov_b32_e32 v21, 0
	v_mov_b32_e32 v89, 0
	s_and_saveexec_b64 s[14:15], s[84:85]
	s_cbranch_execz .LBB0_446
	v_mad_u64_u32 v[18:19], s[8:9], v100, s42, v[22:23]
	v_mad_i32_i24 v19, v101, s42, v19
	global_load_dwordx4 v[18:21], v[18:19], off
.LBB0_446:
	s_or_b64 exec, exec, s[14:15]
	s_waitcnt vmcnt(0)
	s_mov_b64 s[14:15], exec
	s_and_b64 exec, s[14:15], s[80:81]
	v_mov_b32_e32 v1, v14
	v_mov_b32_e32 v24, v15
	v_mov_b32_e32 v25, v16
	v_mov_b32_e32 v26, v17
	s_and_b64 exec, s[14:15], s[82:83]
	v_mov_b32_e32 v27, v10
	v_mov_b32_e32 v29, v11
	v_mov_b32_e32 v28, v12
	v_mov_b32_e32 v30, v13
	s_and_b64 exec, s[14:15], s[84:85]
	v_mov_b32_e32 v31, v18
	v_mov_b32_e32 v32, v19
	v_mov_b32_e32 v33, v20
	v_mov_b32_e32 v89, v21
	s_mov_b64 exec, s[14:15]
	s_lshl_b32 s3, s37, 8
	s_add_i32 s14, s12, s3
	s_ashr_i32 s15, s14, 31
	s_lshl_b64 s[8:9], s[14:15], 14
	v_lshl_add_u64 v[22:23], v[94:95], 0, s[8:9]
	v_mov_b32_e32 v85, v213
	v_lshl_add_u64 v[22:23], v[22:23], 0, v[84:85]
	v_lshl_add_u64 v[102:103], v[22:23], 0, s[44:45]
	v_mov_b64_e32 v[22:23], s[62:63]
	flat_load_dwordx2 v[22:23], v[22:23] offset:24
	v_lshlrev_b32_e32 v212, 2, v87
	v_and_b32_e32 v141, 0xffff0000, v24
	v_and_b32_e32 v121, 0xffff0000, v25
	v_and_b32_e32 v123, 0xffff0000, v26
	s_waitcnt vmcnt(0)
	v_lshlrev_b32_e32 v132, 16, v2
	v_lshlrev_b32_e32 v136, 16, v3
	v_and_b32_e32 v133, 0xffff0000, v2
	v_and_b32_e32 v137, 0xffff0000, v3
	v_lshlrev_b32_e32 v116, 16, v4
	v_lshlrev_b32_e32 v118, 16, v5
	v_and_b32_e32 v117, 0xffff0000, v4
	v_and_b32_e32 v119, 0xffff0000, v5
	v_and_b32_e32 v145, 0xffff0000, v27
	v_lshlrev_b32_e32 v112, 16, v8
	v_lshlrev_b32_e32 v114, 16, v9
	v_and_b32_e32 v113, 0xffff0000, v8
	v_and_b32_e32 v115, 0xffff0000, v9
	v_lshlrev_b32_e32 v130, 16, v6
	v_lshlrev_b32_e32 v134, 16, v7
	v_and_b32_e32 v131, 0xffff0000, v6
	v_and_b32_e32 v135, 0xffff0000, v7
	v_and_b32_e32 v125, 0xffff0000, v30
	v_lshlrev_b32_e32 v142, 16, v11
	v_lshlrev_b32_e32 v144, 16, v10
	v_lshlrev_b32_e32 v124, 16, v13
	v_lshlrev_b32_e32 v126, 16, v12
	v_and_b32_e32 v127, 0xffff0000, v28
	v_lshlrev_b32_e32 v28, 16, v19
	v_and_b32_e32 v19, 0xffff0000, v31
	v_lshlrev_b32_e32 v138, 16, v14
	v_lshlrev_b32_e32 v140, 16, v15
	v_lshlrev_b32_e32 v120, 16, v16
	v_lshlrev_b32_e32 v122, 16, v17
	v_and_b32_e32 v139, 0xffff0000, v1
	ds_read_b32 v1, v161
	v_and_b32_e32 v143, 0xffff0000, v29
	v_and_b32_e32 v29, 0xffff0000, v32
	v_and_b32_e32 v149, 0xffff0000, v33
	v_lshlrev_b32_e32 v18, 16, v18
	v_lshlrev_b32_e32 v148, 16, v20
	v_lshlrev_b32_e32 v150, 16, v21
	s_waitcnt lgkmcnt(0)
	v_mul_f32_e32 v1, 0x3fb8aa3b, v1
	v_exp_f32_e32 v106, v1
	v_and_b32_e32 v151, 0xffff0000, v89
	v_lshl_add_u64 v[104:105], v[46:47], 1, v[102:103]
	v_lshl_add_u64 v[22:23], v[22:23], 0, v[212:213]
	v_add_co_u32_e32 v24, vcc, s71, v22
	flat_load_dwordx4 v[2:5], v[22:23]
	s_nop 0
	v_addc_co_u32_e32 v25, vcc, 0, v23, vcc
	v_add_co_u32_e32 v26, vcc, s13, v22
	flat_load_dwordx4 v[6:9], v[24:25]
	s_nop 0
	v_addc_co_u32_e32 v27, vcc, 0, v23, vcc
	v_add_co_u32_e32 v30, vcc, s93, v22
	flat_load_dwordx4 v[10:13], v[26:27]
	s_nop 0
	v_addc_co_u32_e32 v31, vcc, 0, v23, vcc
	flat_load_dwordx4 v[14:17], v[30:31]
	s_waitcnt vmcnt(0) lgkmcnt(0)
; __device__ __forceinline__ float bflo(unsigned w) { return __uint_as_float(w << 16); }
; __device__ __forceinline__ float bfhi(unsigned w) { return __uint_as_float(w & 0xffff0000u); }
; __device__ __forceinline__ float sigmoidf_(float x) { return __frcp_rn(1.f + __expf(-x)); }
; __device__ __forceinline__ void prepB(const Params& p, int h, int n, char* shmc, int tid, int wv) {
;     ...
;       float out[2][8];
; #pragma unroll
;       for (int tt = 0; tt < 2; ++tt)
; #pragma unroll
;         for (int i = 0; i < 8; ++i) out[tt][i] = 0.f;
; #pragma unroll
;       for (int rr = 0; rr < 5; ++rr) {
;         const uint4 raw = rawv[rr];
;         const unsigned rw[4] = {raw.x, raw.y, raw.z, raw.w};
;         float xv[8];
; #pragma unroll
;         for (int i = 0; i < 4; ++i) { xv[2 * i] = bflo(rw[i]); xv[2 * i + 1] = bfhi(rw[i]); }
; #pragma unroll
;         for (int tt = 0; tt < 2; ++tt) {
;           const int j = rr - tt;
;           if (j >= 0 && j < 4) {
; #pragma unroll
;             for (int i = 0; i < 8; ++i) out[tt][i] += w[j][i] * xv[i];
;           }
;         }
;       }
; #pragma unroll
;       for (int tt = 0; tt < 2; ++tt) {
;         const int t = t0 + tt;
;         float ss = 0.f;
; #pragma unroll
;         for (int i = 0; i < 8; ++i) { const float o = out[tt][i]; out[tt][i] = o * sigmoidf_(o); ss += out[tt][i] * out[tt][i]; }
	v_pk_fma_f32 v[32:33], v[2:3], v[132:133], 0 op_sel_hi:[1,1,0]
	v_pk_fma_f32 v[20:21], v[4:5], v[136:137], 0 op_sel_hi:[1,1,0]
	v_pk_fma_f32 v[2:3], v[2:3], v[130:131], 0 op_sel_hi:[1,1,0]
	v_pk_fma_f32 v[4:5], v[4:5], v[134:135], 0 op_sel_hi:[1,1,0]
	v_pk_fma_f32 v[32:33], v[6:7], v[138:139], v[32:33]
	v_pk_fma_f32 v[20:21], v[8:9], v[140:141], v[20:21]
	v_pk_fma_f32 v[2:3], v[6:7], v[132:133], v[2:3]
	v_pk_fma_f32 v[4:5], v[8:9], v[136:137], v[4:5]
	v_pk_fma_f32 v[32:33], v[10:11], v[144:145], v[32:33]
	v_pk_fma_f32 v[20:21], v[12:13], v[142:143], v[20:21]
	v_pk_fma_f32 v[2:3], v[10:11], v[138:139], v[2:3]
	v_pk_fma_f32 v[18:19], v[14:15], v[18:19], v[32:33]
	v_pk_fma_f32 v[20:21], v[16:17], v[28:29], v[20:21]
	v_mul_f32_e32 v1, 0xbfb8aa3b, v18
	v_exp_f32_e32 v28, v1
	v_mul_f32_e32 v1, 0xbfb8aa3b, v19
	v_exp_f32_e32 v29, v1
	v_mul_f32_e32 v1, 0xbfb8aa3b, v20
	v_exp_f32_e32 v32, v1
	v_mul_f32_e32 v1, 0xbfb8aa3b, v21
	v_exp_f32_e32 v33, v1
	v_pk_add_f32 v[28:29], v[28:29], 1.0 op_sel_hi:[1,0]
	v_pk_fma_f32 v[2:3], v[14:15], v[144:145], v[2:3]
	v_pk_fma_f32 v[4:5], v[12:13], v[140:141], v[4:5]
	v_pk_add_f32 v[32:33], v[32:33], 1.0 op_sel_hi:[1,0]
	v_pk_fma_f32 v[4:5], v[16:17], v[142:143], v[4:5]
	v_div_scale_f32 v1, s[8:9], v33, v33, 1.0
	v_rcp_f32_e32 v85, v1
	s_nop 0
	v_fma_f32 v89, -v1, v85, 1.0
	v_fmac_f32_e32 v85, v89, v85
	v_div_scale_f32 v89, vcc, 1.0, v33, 1.0
	v_mul_f32_e32 v91, v89, v85
	v_fma_f32 v93, -v1, v91, v89
	v_fmac_f32_e32 v91, v93, v85
	v_fma_f32 v1, -v1, v91, v89
	v_div_fmas_f32 v1, v1, v85, v91
	v_div_fixup_f32 v33, v1, v33, 1.0
	v_div_scale_f32 v1, s[8:9], v32, v32, 1.0
	v_rcp_f32_e32 v85, v1
	s_nop 0
	v_fma_f32 v89, -v1, v85, 1.0
	v_fmac_f32_e32 v85, v89, v85
	v_div_scale_f32 v89, vcc, 1.0, v32, 1.0
	v_mul_f32_e32 v91, v89, v85
	v_fma_f32 v93, -v1, v91, v89
	v_fmac_f32_e32 v91, v93, v85
	v_fma_f32 v1, -v1, v91, v89
	v_div_fmas_f32 v1, v1, v85, v91
	v_div_fixup_f32 v32, v1, v32, 1.0
	v_div_scale_f32 v1, s[8:9], v29, v29, 1.0
	v_rcp_f32_e32 v85, v1
	v_pk_mul_f32 v[110:111], v[20:21], v[32:33]
	v_fma_f32 v89, -v1, v85, 1.0
	v_fmac_f32_e32 v85, v89, v85
	v_div_scale_f32 v89, vcc, 1.0, v29, 1.0
	v_mul_f32_e32 v91, v89, v85
	v_fma_f32 v93, -v1, v91, v89
	v_fmac_f32_e32 v91, v93, v85
	v_fma_f32 v1, -v1, v91, v89
	v_div_fmas_f32 v1, v1, v85, v91
	v_div_fixup_f32 v29, v1, v29, 1.0
	v_div_scale_f32 v1, s[8:9], v28, v28, 1.0
	v_rcp_f32_e32 v85, v1
	v_pk_mul_f32 v[128:129], v[110:111], v[110:111]
	v_fma_f32 v89, -v1, v85, 1.0
	v_fmac_f32_e32 v85, v89, v85
	v_div_scale_f32 v89, vcc, 1.0, v28, 1.0
	v_mul_f32_e32 v91, v89, v85
	v_fma_f32 v93, -v1, v91, v89
	v_fmac_f32_e32 v91, v93, v85
	v_fma_f32 v1, -v1, v91, v89
	v_div_fmas_f32 v1, v1, v85, v91
	v_div_fixup_f32 v28, v1, v28, 1.0
	v_pk_mul_f32 v[108:109], v[18:19], v[28:29]
	flat_load_dwordx4 v[18:21], v[22:23] offset:16
	s_nop 0
	flat_load_dwordx4 v[22:25], v[24:25] offset:16
	s_nop 0
	flat_load_dwordx4 v[26:29], v[26:27] offset:16
	s_nop 0
	flat_load_dwordx4 v[30:33], v[30:31] offset:16
	v_pk_mul_f32 v[146:147], v[108:109], v[108:109]
	s_waitcnt vmcnt(0) lgkmcnt(0)
	v_pk_fma_f32 v[154:155], v[18:19], v[116:117], 0 op_sel_hi:[1,1,0]
	s_nop 0
	v_pk_fma_f32 v[154:155], v[22:23], v[120:121], v[154:155]
	v_pk_fma_f32 v[152:153], v[20:21], v[118:119], 0 op_sel_hi:[1,1,0]
	v_pk_fma_f32 v[154:155], v[26:27], v[126:127], v[154:155]
	v_pk_fma_f32 v[152:153], v[24:25], v[122:123], v[152:153]
	v_pk_fma_f32 v[148:149], v[30:31], v[148:149], v[154:155]
	v_pk_fma_f32 v[152:153], v[28:29], v[124:125], v[152:153]
	v_mul_f32_e32 v1, 0xbfb8aa3b, v148
	v_pk_fma_f32 v[150:151], v[32:33], v[150:151], v[152:153]
	v_exp_f32_e32 v152, v1
	v_mul_f32_e32 v1, 0xbfb8aa3b, v149
	v_exp_f32_e32 v153, v1
	v_mul_f32_e32 v1, 0xbfb8aa3b, v150
	v_exp_f32_e32 v154, v1
	v_mul_f32_e32 v1, 0xbfb8aa3b, v151
	v_exp_f32_e32 v155, v1
	v_pk_add_f32 v[152:153], v[152:153], 1.0 op_sel_hi:[1,0]
	v_pk_add_f32 v[154:155], v[154:155], 1.0 op_sel_hi:[1,0]
	s_nop 0
	v_div_scale_f32 v1, s[8:9], v155, v155, 1.0
	v_rcp_f32_e32 v85, v1
	s_nop 0
	v_fma_f32 v89, -v1, v85, 1.0
	v_fmac_f32_e32 v85, v89, v85
	v_div_scale_f32 v89, vcc, 1.0, v155, 1.0
	v_mul_f32_e32 v91, v89, v85
	v_fma_f32 v93, -v1, v91, v89
	v_fmac_f32_e32 v91, v93, v85
	v_fma_f32 v1, -v1, v91, v89
	v_div_fmas_f32 v1, v1, v85, v91
	v_div_fixup_f32 v155, v1, v155, 1.0
	v_div_scale_f32 v1, s[8:9], v154, v154, 1.0
	v_rcp_f32_e32 v85, v1
	s_nop 0
	v_fma_f32 v89, -v1, v85, 1.0
	v_fmac_f32_e32 v85, v89, v85
	v_div_scale_f32 v89, vcc, 1.0, v154, 1.0
	v_mul_f32_e32 v91, v89, v85
	v_fma_f32 v93, -v1, v91, v89
	v_fmac_f32_e32 v91, v93, v85
	v_fma_f32 v1, -v1, v91, v89
	v_div_fmas_f32 v1, v1, v85, v91
	v_div_fixup_f32 v154, v1, v154, 1.0
	v_div_scale_f32 v1, s[8:9], v153, v153, 1.0
	v_rcp_f32_e32 v85, v1
	v_pk_mul_f32 v[150:151], v[150:151], v[154:155]
	v_fma_f32 v89, -v1, v85, 1.0
	v_fmac_f32_e32 v85, v89, v85
	v_div_scale_f32 v89, vcc, 1.0, v153, 1.0
	v_mul_f32_e32 v91, v89, v85
	v_fma_f32 v93, -v1, v91, v89
	v_fmac_f32_e32 v91, v93, v85
	v_fma_f32 v1, -v1, v91, v89
	v_div_fmas_f32 v1, v1, v85, v91
	v_div_fixup_f32 v153, v1, v153, 1.0
	v_div_scale_f32 v1, s[8:9], v152, v152, 1.0
	v_rcp_f32_e32 v85, v1
	s_nop 0
	v_fma_f32 v89, -v1, v85, 1.0
	v_fmac_f32_e32 v85, v89, v85
	v_div_scale_f32 v89, vcc, 1.0, v152, 1.0
	v_mul_f32_e32 v91, v89, v85
	v_fma_f32 v93, -v1, v91, v89
	v_fmac_f32_e32 v91, v93, v85
	v_fma_f32 v1, -v1, v91, v89
	v_div_fmas_f32 v1, v1, v85, v91
	v_div_fixup_f32 v152, v1, v152, 1.0
	v_mul_f32_e32 v1, 0xbfb8aa3b, v2
	v_exp_f32_e32 v6, v1
	v_mul_f32_e32 v1, 0xbfb8aa3b, v3
	v_exp_f32_e32 v7, v1
	v_mul_f32_e32 v1, 0xbfb8aa3b, v4
	v_exp_f32_e32 v8, v1
; __device__ __forceinline__ float shfl_idx(float v, int srclane) { return __int_as_float(__builtin_amdgcn_ds_bpermute(srclane << 2, __float_as_int(v))); }
; __device__ __forceinline__ float sigmoidf_(float x) { return __frcp_rn(1.f + __expf(-x)); }
; __device__ __forceinline__ void prepB(const Params& p, int h, int n, char* shmc, int tid, int wv) {
;     ...
;       for (int tt = 0; tt < 2; ++tt) {
;         const int t = t0 + tt;
;         float ss = 0.f;
; #pragma unroll
;         for (int i = 0; i < 8; ++i) { const float o = out[tt][i]; out[tt][i] = o * sigmoidf_(o); ss += out[tt][i] * out[tt][i]; }
;         if (sig < 2) {
; #pragma unroll
;           for (int o = 1; o < 16; o <<= 1) ss += shfl_idx(ss, (tid & 63) ^ o);
	v_mul_f32_e32 v1, 0xbfb8aa3b, v5
	v_exp_f32_e32 v9, v1
	v_pk_add_f32 v[6:7], v[6:7], 1.0 op_sel_hi:[1,0]
	v_pk_mul_f32 v[148:149], v[148:149], v[152:153]
	v_pk_mul_f32 v[152:153], v[150:151], v[150:151]
	v_pk_add_f32 v[8:9], v[8:9], 1.0 op_sel_hi:[1,0]
	v_pk_mul_f32 v[154:155], v[148:149], v[148:149]
	v_div_scale_f32 v1, s[8:9], v9, v9, 1.0
	v_rcp_f32_e32 v10, v1
	s_nop 0
	v_fma_f32 v11, -v1, v10, 1.0
	v_fmac_f32_e32 v10, v11, v10
	v_div_scale_f32 v11, vcc, 1.0, v9, 1.0
	v_mul_f32_e32 v12, v11, v10
	v_fma_f32 v13, -v1, v12, v11
	v_fmac_f32_e32 v12, v13, v10
	v_fma_f32 v1, -v1, v12, v11
	v_div_fmas_f32 v1, v1, v10, v12
	v_div_fixup_f32 v9, v1, v9, 1.0
	v_div_scale_f32 v1, s[8:9], v8, v8, 1.0
	v_rcp_f32_e32 v10, v1
	s_nop 0
	v_fma_f32 v11, -v1, v10, 1.0
	v_fmac_f32_e32 v10, v11, v10
	v_div_scale_f32 v11, vcc, 1.0, v8, 1.0
	v_mul_f32_e32 v12, v11, v10
	v_fma_f32 v13, -v1, v12, v11
	v_fmac_f32_e32 v12, v13, v10
	v_fma_f32 v1, -v1, v12, v11
	v_div_fmas_f32 v1, v1, v10, v12
	v_div_fixup_f32 v8, v1, v8, 1.0
	v_div_scale_f32 v1, s[8:9], v7, v7, 1.0
	v_rcp_f32_e32 v10, v1
	v_pk_mul_f32 v[4:5], v[4:5], v[8:9]
	v_fma_f32 v11, -v1, v10, 1.0
	v_fmac_f32_e32 v10, v11, v10
	v_div_scale_f32 v11, vcc, 1.0, v7, 1.0
	v_mul_f32_e32 v12, v11, v10
	v_fma_f32 v13, -v1, v12, v11
	v_fmac_f32_e32 v12, v13, v10
	v_fma_f32 v1, -v1, v12, v11
	v_div_fmas_f32 v1, v1, v10, v12
	v_div_fixup_f32 v7, v1, v7, 1.0
	v_div_scale_f32 v1, s[8:9], v6, v6, 1.0
	v_rcp_f32_e32 v10, v1
	s_nop 0
	v_fma_f32 v11, -v1, v10, 1.0
	v_fmac_f32_e32 v10, v11, v10
	v_div_scale_f32 v11, vcc, 1.0, v6, 1.0
	v_mul_f32_e32 v12, v11, v10
	v_fma_f32 v13, -v1, v12, v11
	v_fmac_f32_e32 v12, v13, v10
	v_fma_f32 v1, -v1, v12, v11
	v_div_fmas_f32 v1, v1, v10, v12
	v_div_fixup_f32 v6, v1, v6, 1.0
	v_pk_mul_f32 v[2:3], v[2:3], v[6:7]
	v_pk_fma_f32 v[12:13], v[18:19], v[112:113], 0 op_sel_hi:[1,1,0]
	v_pk_mul_f32 v[8:9], v[2:3], v[2:3]
	v_mov_b32_e32 v10, v146
	v_mov_b32_e32 v11, v8
	v_mov_b32_e32 v8, v147
	v_pk_fma_f32 v[12:13], v[22:23], v[116:117], v[12:13]
	v_pk_add_f32 v[8:9], v[10:11], v[8:9]
	v_pk_fma_f32 v[10:11], v[20:21], v[114:115], 0 op_sel_hi:[1,1,0]
	v_pk_fma_f32 v[12:13], v[26:27], v[120:121], v[12:13]
	v_pk_fma_f32 v[10:11], v[24:25], v[118:119], v[10:11]
	v_pk_fma_f32 v[12:13], v[30:31], v[126:127], v[12:13]
	v_pk_fma_f32 v[10:11], v[28:29], v[122:123], v[10:11]
	v_mul_f32_e32 v1, 0xbfb8aa3b, v12
	v_pk_fma_f32 v[10:11], v[32:33], v[124:125], v[10:11]
	v_exp_f32_e32 v14, v1
	v_mul_f32_e32 v1, 0xbfb8aa3b, v13
	v_exp_f32_e32 v15, v1
	v_mul_f32_e32 v1, 0xbfb8aa3b, v10
	v_exp_f32_e32 v16, v1
	v_mul_f32_e32 v1, 0xbfb8aa3b, v11
	v_exp_f32_e32 v17, v1
	v_pk_add_f32 v[14:15], v[14:15], 1.0 op_sel_hi:[1,0]
	v_pk_mul_f32 v[6:7], v[4:5], v[4:5]
	v_mov_b32_e32 v22, 0
	v_pk_add_f32 v[16:17], v[16:17], 1.0 op_sel_hi:[1,0]
	v_mov_b32_e32 v23, 0
	v_div_scale_f32 v1, s[8:9], v17, v17, 1.0
	v_rcp_f32_e32 v18, v1
	v_mov_b32_e32 v24, 0
	v_mov_b32_e32 v25, 0
	v_fma_f32 v19, -v1, v18, 1.0
	v_fmac_f32_e32 v18, v19, v18
	v_div_scale_f32 v19, vcc, 1.0, v17, 1.0
	v_mul_f32_e32 v20, v19, v18
	v_fma_f32 v21, -v1, v20, v19
	v_fmac_f32_e32 v20, v21, v18
	v_fma_f32 v1, -v1, v20, v19
	v_div_fmas_f32 v1, v1, v18, v20
	v_div_fixup_f32 v17, v1, v17, 1.0
	v_div_scale_f32 v1, s[8:9], v16, v16, 1.0
	v_rcp_f32_e32 v18, v1
	s_nop 0
	v_fma_f32 v19, -v1, v18, 1.0
	v_fmac_f32_e32 v18, v19, v18
	v_div_scale_f32 v19, vcc, 1.0, v16, 1.0
	v_mul_f32_e32 v20, v19, v18
	v_fma_f32 v21, -v1, v20, v19
	v_fmac_f32_e32 v20, v21, v18
	v_fma_f32 v1, -v1, v20, v19
	v_div_fmas_f32 v1, v1, v18, v20
	v_div_fixup_f32 v16, v1, v16, 1.0
	v_div_scale_f32 v1, s[8:9], v15, v15, 1.0
	v_rcp_f32_e32 v18, v1
	v_pk_mul_f32 v[10:11], v[10:11], v[16:17]
	v_fma_f32 v19, -v1, v18, 1.0
	v_fmac_f32_e32 v18, v19, v18
	v_div_scale_f32 v19, vcc, 1.0, v15, 1.0
	v_mul_f32_e32 v20, v19, v18
	v_fma_f32 v21, -v1, v20, v19
	v_fmac_f32_e32 v20, v21, v18
	v_fma_f32 v1, -v1, v20, v19
	v_div_fmas_f32 v1, v1, v18, v20
	v_div_fixup_f32 v15, v1, v15, 1.0
	v_div_scale_f32 v1, s[8:9], v14, v14, 1.0
	v_rcp_f32_e32 v18, v1
	s_mov_b32 s8, 0x358637bd
	v_fma_f32 v19, -v1, v18, 1.0
	v_fmac_f32_e32 v18, v19, v18
	v_div_scale_f32 v19, vcc, 1.0, v14, 1.0
	v_mul_f32_e32 v20, v19, v18
	v_fma_f32 v21, -v1, v20, v19
	v_fmac_f32_e32 v20, v21, v18
	v_fma_f32 v1, -v1, v20, v19
	v_div_fmas_f32 v1, v1, v18, v20
	v_div_fixup_f32 v14, v1, v14, 1.0
	v_pk_mul_f32 v[12:13], v[12:13], v[14:15]
	v_mov_b32_e32 v18, v128
	v_mov_b32_e32 v19, v6
	v_pk_mul_f32 v[16:17], v[12:13], v[12:13]
	v_pk_add_f32 v[8:9], v[8:9], v[18:19]
	v_mov_b32_e32 v6, v129
	v_pk_add_f32 v[6:7], v[8:9], v[6:7]
	v_mov_b32_e32 v8, v154
	v_mov_b32_e32 v9, v16
	v_pk_mul_f32 v[14:15], v[10:11], v[10:11]
	v_pk_add_f32 v[6:7], v[6:7], v[8:9]
	v_mov_b32_e32 v16, v155
	v_pk_add_f32 v[6:7], v[6:7], v[16:17]
	v_mov_b32_e32 v8, v152
	v_mov_b32_e32 v9, v14
	v_pk_add_f32 v[6:7], v[6:7], v[8:9]
	v_mov_b32_e32 v14, v153
	v_pk_add_f32 v[6:7], v[6:7], v[14:15]
	ds_bpermute_b32 v9, v157, v7
	ds_bpermute_b32 v8, v157, v6
	v_or_b32_e32 v20, 0x400, v87
	s_waitcnt lgkmcnt(0)
	v_pk_add_f32 v[6:7], v[6:7], v[8:9]
	ds_bpermute_b32 v9, v158, v7
	ds_bpermute_b32 v8, v158, v6
	s_waitcnt lgkmcnt(0)
	v_pk_add_f32 v[6:7], v[6:7], v[8:9]
	ds_bpermute_b32 v9, v159, v7
	ds_bpermute_b32 v8, v159, v6
	s_waitcnt lgkmcnt(0)
	v_pk_add_f32 v[6:7], v[6:7], v[8:9]
	ds_bpermute_b32 v9, v160, v7
	ds_bpermute_b32 v8, v160, v6
	s_waitcnt lgkmcnt(0)
; __device__ __forceinline__ unsigned pack2(float a, float b) { const f32v2_ v = {a, b}; const bf16v2_ r = __builtin_convertvector(v, bf16v2_); return __builtin_bit_cast(unsigned, r); }
; __device__ __forceinline__ float shfl_idx(float v, int srclane) { return __int_as_float(__builtin_amdgcn_ds_bpermute(srclane << 2, __float_as_int(v))); }
; __device__ __forceinline__ uint4 ldg16(const void* p) { const u32x4 v = *(const __attribute__((address_space(1))) u32x4*)(p); return make_uint4(v.x, v.y, v.z, v.w); }
; __device__ __forceinline__ int perm32(int c) { return ((c >> 2) & 3) * 8 + ((c >> 4) & 1) * 4 + (c & 3); }
; __device__ __forceinline__ void prepB(const Params& p, int h, int n, char* shmc, int tid, int wv) {
;     ...
;       for (int rr = 0; rr < 5; ++rr) {
;         const long tok = rowbase + t0 - 3 + rr;
;         rawv[rr] = make_uint4(0u, 0u, 0u, 0u);
;         if (tok >= 0) rawv[rr] = ldg16(GQKV + tok * 3072 + colg);
;       }
;     ...
;         if (sig < 2) {
; #pragma unroll
;           for (int o = 1; o < 16; o <<= 1) ss += shfl_idx(ss, (tid & 63) ^ o);
;           const float rs = rsqrtf(ss + EPS_);
;           if (sig == 0) {
;             const float eg = __expf(gcS[t]);
;             float qn[8];
; #pragma unroll
;             for (int i = 0; i < 8; ++i) { qn[i] = out[tt][i] * rs * 0.08838834764831845f; qB[t * 136 + c0 + i] = f2bf(qn[i]); }
;             u16* qd = QPB + (long)tix * 8192;
; #pragma unroll
;             for (int g = 0; g < 2; ++g) {
;               uint2 o; o.x = pack2(qn[4 * g] * eg, qn[4 * g + 1] * eg); o.y = pack2(qn[4 * g + 2] * eg, qn[4 * g + 3] * eg);
;               const int p0 = (c0 & ~31) + perm32((c0 & 31) + 4 * g);
;               *(uint2*)(qd + ((((t >> 4) * 4 + (p0 >> 5)) * 64 + ((p0 >> 3) & 3) * 16 + (t & 15)) * 8) + (p0 & 7)) = o;
;             }
	v_pk_add_f32 v[6:7], v[6:7], v[8:9]
	s_nop 0
	v_pk_add_f32 v[6:7], v[6:7], s[8:9] op_sel_hi:[1,0]
	s_nop 0
	v_mul_f32_e32 v1, 0x4b800000, v7
	v_cmp_gt_f32_e64 s[86:87], s70, v7
	v_cmp_gt_f32_e32 vcc, s70, v6
	s_nop 0
	v_cndmask_b32_e64 v1, v7, v1, s[86:87]
	v_rsq_f32_e32 v1, v1
	s_nop 0
	v_mul_f32_e32 v7, 0x45800000, v1
	v_cndmask_b32_e64 v8, v1, v7, s[86:87]
	v_pk_mul_f32 v[2:3], v[2:3], v[8:9] op_sel_hi:[1,0]
	v_pk_mul_f32 v[4:5], v[4:5], v[8:9] op_sel_hi:[1,0]
	v_pk_mul_f32 v[16:17], v[2:3], s[56:57] op_sel_hi:[1,0]
	v_pk_mul_f32 v[14:15], v[4:5], s[56:57] op_sel_hi:[1,0]
	v_pk_mul_f32 v[2:3], v[12:13], v[8:9] op_sel_hi:[1,0]
	v_pk_mul_f32 v[4:5], v[10:11], v[8:9] op_sel_hi:[1,0]
	v_pk_mul_f32 v[10:11], v[2:3], s[56:57] op_sel_hi:[1,0]
	v_pk_mul_f32 v[8:9], v[4:5], s[56:57] op_sel_hi:[1,0]
	v_add_u32_e32 v1, v156, v162
	v_cvt_pk_bf16_f32 v5, v8, v9
	v_cvt_pk_bf16_f32 v4, v10, v11
	v_cvt_pk_bf16_f32 v3, v14, v15
	v_cvt_pk_bf16_f32 v2, v16, v17
	ds_write_b128 v1, v[2:5]
	v_mul_f32_e32 v1, 0x4b800000, v6
	v_cndmask_b32_e32 v1, v6, v1, vcc
	v_pk_mul_f32 v[2:3], v[106:107], v[16:17] op_sel_hi:[0,1]
	v_pk_mul_f32 v[4:5], v[106:107], v[14:15] op_sel_hi:[0,1]
	v_rsq_f32_e32 v1, v1
	v_cvt_pk_bf16_f32 v2, v2, v3
	v_cvt_pk_bf16_f32 v3, v4, v5
	flat_store_dwordx2 v[104:105], v[2:3]
	v_pk_mul_f32 v[2:3], v[106:107], v[10:11] op_sel_hi:[0,1]
	v_pk_mul_f32 v[4:5], v[106:107], v[8:9] op_sel_hi:[0,1]
	v_cvt_pk_bf16_f32 v2, v2, v3
	v_cvt_pk_bf16_f32 v3, v4, v5
	flat_store_dwordx2 v[104:105], v[2:3] offset:256
	v_mul_f32_e32 v2, 0x45800000, v1
	v_cndmask_b32_e32 v2, v1, v2, vcc
	ds_read_b32 v1, v163
	v_pk_mul_f32 v[4:5], v[108:109], v[2:3] op_sel_hi:[1,0]
	v_pk_mul_f32 v[6:7], v[110:111], v[2:3] op_sel_hi:[1,0]
	v_pk_mul_f32 v[8:9], v[4:5], s[56:57] op_sel_hi:[1,0]
	v_pk_mul_f32 v[4:5], v[148:149], v[2:3] op_sel_hi:[1,0]
	v_pk_mul_f32 v[2:3], v[150:151], v[2:3] op_sel_hi:[1,0]
	v_pk_mul_f32 v[6:7], v[6:7], s[56:57] op_sel_hi:[1,0]
	v_pk_mul_f32 v[10:11], v[2:3], s[56:57] op_sel_hi:[1,0]
	v_pk_mul_f32 v[12:13], v[4:5], s[56:57] op_sel_hi:[1,0]
	s_waitcnt lgkmcnt(0)
	v_mul_f32_e32 v1, 0x3fb8aa3b, v1
	v_add_u32_e32 v14, v156, v164
	v_cvt_pk_bf16_f32 v5, v10, v11
	v_cvt_pk_bf16_f32 v4, v12, v13
	v_cvt_pk_bf16_f32 v3, v6, v7
	v_cvt_pk_bf16_f32 v2, v8, v9
	ds_write_b128 v14, v[2:5]
	v_exp_f32_e32 v2, v1
	v_mov_b32_e32 v1, 0
	v_pk_mul_f32 v[4:5], v[2:3], v[8:9] op_sel_hi:[0,1]
	v_pk_mul_f32 v[6:7], v[2:3], v[6:7] op_sel_hi:[0,1]
	v_cvt_pk_bf16_f32 v4, v4, v5
	v_cvt_pk_bf16_f32 v5, v6, v7
	v_lshl_add_u64 v[6:7], v[48:49], 1, v[102:103]
	flat_store_dwordx2 v[6:7], v[4:5]
	v_pk_mul_f32 v[4:5], v[2:3], v[12:13] op_sel_hi:[0,1]
	v_pk_mul_f32 v[2:3], v[2:3], v[10:11] op_sel_hi:[0,1]
	v_cvt_pk_bf16_f32 v4, v4, v5
	v_cvt_pk_bf16_f32 v5, v2, v3
	v_mov_b32_e32 v2, 0
	v_mov_b32_e32 v3, 0
	flat_store_dwordx2 v[6:7], v[4:5] offset:256
	s_and_saveexec_b64 s[86:87], s[76:77]
	s_cbranch_execz .LBB0_448
	v_mad_u64_u32 v[0:1], s[8:9], v34, s42, v[36:37]
	v_mad_i32_i24 v1, v35, s42, v1
	v_lshlrev_b32_e32 v212, 1, v20
	v_lshl_add_u64 v[0:1], v[0:1], 0, v[212:213]
	global_load_dwordx4 v[0:3], v[0:1], off
.LBB0_448:
	s_or_b64 exec, exec, s[86:87]
	v_mov_b32_e32 v4, 0
	v_mov_b32_e32 v8, 0
	v_mov_b32_e32 v26, 0
	v_mov_b32_e32 v9, 0
	v_mov_b32_e32 v27, 0
	v_mov_b32_e32 v10, 0
	v_mov_b32_e32 v28, 0
	v_mov_b32_e32 v11, 0
	v_mov_b32_e32 v29, 0
	s_and_saveexec_b64 s[86:87], s[78:79]
	s_cbranch_execz .LBB0_450
	v_mad_u64_u32 v[6:7], s[8:9], v38, s42, v[36:37]
	v_mad_i32_i24 v7, v39, s42, v7
	v_lshlrev_b32_e32 v212, 1, v20
	v_lshl_add_u64 v[6:7], v[6:7], 0, v[212:213]
	global_load_dwordx4 v[8:11], v[6:7], off
.LBB0_450:
	s_or_b64 exec, exec, s[86:87]
	v_mov_b32_e32 v30, 0
	v_mov_b32_e32 v5, 0
	v_mov_b32_e32 v31, 0
	v_mov_b32_e32 v6, 0
	v_mov_b32_e32 v85, 0
	v_mov_b32_e32 v7, 0
	v_mov_b32_e32 v89, 0
	s_and_saveexec_b64 s[86:87], s[80:81]
	s_cbranch_execz .LBB0_452
	v_mad_u64_u32 v[4:5], s[8:9], v96, s42, v[36:37]
	v_mad_i32_i24 v5, v97, s42, v5
	v_lshlrev_b32_e32 v212, 1, v20
	v_lshl_add_u64 v[4:5], v[4:5], 0, v[212:213]
	global_load_dwordx4 v[4:7], v[4:5], off
.LBB0_452:
	s_or_b64 exec, exec, s[86:87]
	v_mov_b32_e32 v12, 0
	v_mov_b32_e32 v16, 0
	v_mov_b32_e32 v91, 0
	v_mov_b32_e32 v17, 0
	v_mov_b32_e32 v102, 0
	v_mov_b32_e32 v18, 0
	v_mov_b32_e32 v93, 0
	v_mov_b32_e32 v19, 0
	v_mov_b32_e32 v103, 0
	s_and_saveexec_b64 s[86:87], s[82:83]
	s_cbranch_execz .LBB0_454
	v_mad_u64_u32 v[14:15], s[8:9], v98, s42, v[36:37]
	v_mad_i32_i24 v15, v99, s42, v15
	v_lshlrev_b32_e32 v212, 1, v20
	v_lshl_add_u64 v[14:15], v[14:15], 0, v[212:213]
	global_load_dwordx4 v[16:19], v[14:15], off
.LBB0_454:
	s_or_b64 exec, exec, s[86:87]
	v_mov_b32_e32 v104, 0
	v_mov_b32_e32 v13, 0
	v_mov_b32_e32 v105, 0
	v_mov_b32_e32 v14, 0
	v_mov_b32_e32 v122, 0
	v_mov_b32_e32 v15, 0
	v_mov_b32_e32 v123, 0
	s_and_saveexec_b64 s[86:87], s[84:85]
	s_cbranch_execz .LBB0_456
	v_mad_u64_u32 v[12:13], s[8:9], v100, s42, v[36:37]
	v_mad_i32_i24 v13, v101, s42, v13
	v_lshlrev_b32_e32 v212, 1, v20
	v_lshl_add_u64 v[12:13], v[12:13], 0, v[212:213]
	global_load_dwordx4 v[12:15], v[12:13], off
; __device__ __forceinline__ float bflo(unsigned w) { return __uint_as_float(w << 16); }
; __device__ __forceinline__ float bfhi(unsigned w) { return __uint_as_float(w & 0xffff0000u); }
; __device__ __forceinline__ uint4 ldg16(const void* p) { const u32x4 v = *(const __attribute__((address_space(1))) u32x4*)(p); return make_uint4(v.x, v.y, v.z, v.w); }
; __device__ __forceinline__ float sigmoidf_(float x) { return __frcp_rn(1.f + __expf(-x)); }
; __device__ __forceinline__ void prepB(const Params& p, int h, int n, char* shmc, int tid, int wv) {
;     ...
;       for (int rr = 0; rr < 5; ++rr) {
;         const long tok = rowbase + t0 - 3 + rr;
;         rawv[rr] = make_uint4(0u, 0u, 0u, 0u);
;         if (tok >= 0) rawv[rr] = ldg16(GQKV + tok * 3072 + colg);
;       }
;       float w[4][8];
; #pragma unroll
;       for (int j = 0; j < 4; ++j) {
;         const float4 wa = *(const float4*)(p.a_conv_w + j * 3072 + colg), wb = *(const float4*)(p.a_conv_w + j * 3072 + colg + 4);
;         w[j][0] = wa.x; w[j][1] = wa.y; w[j][2] = wa.z; w[j][3] = wa.w; w[j][4] = wb.x; w[j][5] = wb.y; w[j][6] = wb.z; w[j][7] = wb.w;
;       }
;       float out[2][8];
; #pragma unroll
;       for (int tt = 0; tt < 2; ++tt)
; #pragma unroll
;         for (int i = 0; i < 8; ++i) out[tt][i] = 0.f;
; #pragma unroll
;       for (int rr = 0; rr < 5; ++rr) {
;         const uint4 raw = rawv[rr];
;         const unsigned rw[4] = {raw.x, raw.y, raw.z, raw.w};
;         float xv[8];
; #pragma unroll
;         for (int i = 0; i < 4; ++i) { xv[2 * i] = bflo(rw[i]); xv[2 * i + 1] = bfhi(rw[i]); }
; #pragma unroll
;         for (int tt = 0; tt < 2; ++tt) {
;           const int j = rr - tt;
;           if (j >= 0 && j < 4) {
; #pragma unroll
;             for (int i = 0; i < 8; ++i) out[tt][i] += w[j][i] * xv[i];
;           }
;         }
;       }
; #pragma unroll
;       for (int tt = 0; tt < 2; ++tt) {
;         const int t = t0 + tt;
;         float ss = 0.f;
; #pragma unroll
;         for (int i = 0; i < 8; ++i) { const float o = out[tt][i]; out[tt][i] = o * sigmoidf_(o); ss += out[tt][i] * out[tt][i]; }
.LBB0_456:
	s_or_b64 exec, exec, s[86:87]
	s_waitcnt vmcnt(0)
	s_mov_b64 s[86:87], exec
	s_and_b64 exec, s[86:87], s[76:77]
	v_mov_b32_e32 v22, v0
	v_mov_b32_e32 v23, v1
	v_mov_b32_e32 v24, v2
	v_mov_b32_e32 v25, v3
	s_and_b64 exec, s[86:87], s[78:79]
	v_mov_b32_e32 v26, v8
	v_mov_b32_e32 v27, v9
	v_mov_b32_e32 v28, v10
	v_mov_b32_e32 v29, v11
	s_and_b64 exec, s[86:87], s[80:81]
	v_mov_b32_e32 v30, v4
	v_mov_b32_e32 v31, v5
	v_mov_b32_e32 v85, v6
	v_mov_b32_e32 v89, v7
	s_and_b64 exec, s[86:87], s[82:83]
	v_mov_b32_e32 v91, v16
	v_mov_b32_e32 v102, v17
	v_mov_b32_e32 v93, v18
	v_mov_b32_e32 v103, v19
	s_and_b64 exec, s[86:87], s[84:85]
	v_mov_b32_e32 v104, v12
	v_mov_b32_e32 v105, v13
	v_mov_b32_e32 v122, v14
	v_mov_b32_e32 v123, v15
	s_mov_b64 exec, s[86:87]
	v_mov_b64_e32 v[32:33], s[62:63]
	flat_load_dwordx2 v[32:33], v[32:33] offset:24
	v_lshlrev_b32_e32 v212, 2, v20
	v_and_b32_e32 v125, 0xffff0000, v22
	v_and_b32_e32 v129, 0xffff0000, v23
	v_and_b32_e32 v107, 0xffff0000, v24
	v_lshlrev_b32_e32 v106, 16, v2
	v_lshlrev_b32_e32 v108, 16, v3
	v_and_b32_e32 v109, 0xffff0000, v25
	v_lshlrev_b32_e32 v124, 16, v0
	v_lshlrev_b32_e32 v128, 16, v1
	v_and_b32_e32 v111, 0xffff0000, v28
	v_lshlrev_b32_e32 v132, 16, v4
	v_lshlrev_b32_e32 v134, 16, v5
	v_lshlrev_b32_e32 v114, 16, v6
	v_lshlrev_b32_e32 v116, 16, v7
	v_lshlrev_b32_e32 v126, 16, v8
	v_lshlrev_b32_e32 v130, 16, v9
	v_lshlrev_b32_e32 v110, 16, v10
	v_lshlrev_b32_e32 v112, 16, v11
	v_and_b32_e32 v113, 0xffff0000, v29
	v_lshlrev_b32_e32 v138, 16, v16
	v_lshlrev_b32_e32 v120, 16, v18
	v_lshlrev_b32_e32 v16, 16, v12
	v_lshlrev_b32_e32 v18, 16, v13
	v_lshlrev_b32_e32 v142, 16, v14
	v_lshlrev_b32_e32 v144, 16, v15
	v_and_b32_e32 v131, 0xffff0000, v27
	v_and_b32_e32 v127, 0xffff0000, v26
	v_and_b32_e32 v135, 0xffff0000, v31
	v_and_b32_e32 v133, 0xffff0000, v30
	v_lshlrev_b32_e32 v136, 16, v17
	v_and_b32_e32 v137, 0xffff0000, v102
	v_and_b32_e32 v139, 0xffff0000, v91
	v_lshlrev_b32_e32 v118, 16, v19
	v_and_b32_e32 v19, 0xffff0000, v105
	v_and_b32_e32 v17, 0xffff0000, v104
	v_and_b32_e32 v115, 0xffff0000, v85
	v_and_b32_e32 v117, 0xffff0000, v89
	v_and_b32_e32 v121, 0xffff0000, v93
	v_and_b32_e32 v119, 0xffff0000, v103
	v_and_b32_e32 v143, 0xffff0000, v122
	v_and_b32_e32 v145, 0xffff0000, v123
	s_waitcnt vmcnt(0) lgkmcnt(0)
	v_lshl_add_u64 v[20:21], v[32:33], 0, v[212:213]
	v_add_co_u32_e32 v22, vcc, s71, v20
	flat_load_dwordx4 v[0:3], v[20:21]
	s_nop 0
	v_addc_co_u32_e32 v23, vcc, 0, v21, vcc
	v_add_co_u32_e32 v24, vcc, s13, v20
	flat_load_dwordx4 v[4:7], v[22:23]
	s_nop 0
	v_addc_co_u32_e32 v25, vcc, 0, v21, vcc
	v_add_co_u32_e32 v28, vcc, s93, v20
	flat_load_dwordx4 v[8:11], v[24:25]
	s_nop 0
	v_addc_co_u32_e32 v29, vcc, 0, v21, vcc
	flat_load_dwordx4 v[12:15], v[28:29]
	s_waitcnt vmcnt(0) lgkmcnt(0)
	v_pk_fma_f32 v[26:27], v[2:3], v[130:131], 0 op_sel_hi:[1,1,0]
	v_pk_fma_f32 v[30:31], v[0:1], v[126:127], 0 op_sel_hi:[1,1,0]
	v_pk_fma_f32 v[2:3], v[2:3], v[128:129], 0 op_sel_hi:[1,1,0]
	v_pk_fma_f32 v[0:1], v[0:1], v[124:125], 0 op_sel_hi:[1,1,0]
	v_pk_fma_f32 v[26:27], v[6:7], v[134:135], v[26:27]
	v_pk_fma_f32 v[30:31], v[4:5], v[132:133], v[30:31]
	v_pk_fma_f32 v[2:3], v[6:7], v[130:131], v[2:3]
	v_pk_fma_f32 v[0:1], v[4:5], v[126:127], v[0:1]
	v_pk_fma_f32 v[26:27], v[10:11], v[136:137], v[26:27]
	v_pk_fma_f32 v[30:31], v[8:9], v[138:139], v[30:31]
	v_pk_fma_f32 v[2:3], v[10:11], v[134:135], v[2:3]
	v_pk_fma_f32 v[18:19], v[14:15], v[18:19], v[26:27]
	v_pk_fma_f32 v[16:17], v[12:13], v[16:17], v[30:31]
	v_mul_f32_e32 v30, 0xbfb8aa3b, v18
	v_mul_f32_e32 v31, 0xbfb8aa3b, v19
	v_exp_f32_e32 v30, v30
	v_exp_f32_e32 v31, v31
	v_mul_f32_e32 v26, 0xbfb8aa3b, v16
	v_mul_f32_e32 v27, 0xbfb8aa3b, v17
	v_exp_f32_e32 v26, v26
	v_pk_add_f32 v[30:31], v[30:31], 1.0 op_sel_hi:[1,0]
	v_exp_f32_e32 v27, v27
	v_div_scale_f32 v85, s[8:9], v31, v31, 1.0
	v_rcp_f32_e32 v89, v85
	v_pk_add_f32 v[26:27], v[26:27], 1.0 op_sel_hi:[1,0]
	v_pk_fma_f32 v[2:3], v[14:15], v[136:137], v[2:3]
	v_pk_fma_f32 v[0:1], v[8:9], v[132:133], v[0:1]
	v_fma_f32 v91, -v85, v89, 1.0
	v_fmac_f32_e32 v89, v91, v89
	v_div_scale_f32 v91, vcc, 1.0, v31, 1.0
	v_mul_f32_e32 v93, v91, v89
	v_fma_f32 v102, -v85, v93, v91
	v_fmac_f32_e32 v93, v102, v89
	v_fma_f32 v85, -v85, v93, v91
	v_div_fmas_f32 v85, v85, v89, v93
	v_div_fixup_f32 v31, v85, v31, 1.0
	v_div_scale_f32 v85, s[8:9], v30, v30, 1.0
	v_rcp_f32_e32 v89, v85
	v_mul_f32_e32 v6, 0xbfb8aa3b, v2
	v_mul_f32_e32 v7, 0xbfb8aa3b, v3
	v_exp_f32_e32 v6, v6
	v_fma_f32 v91, -v85, v89, 1.0
	v_fmac_f32_e32 v89, v91, v89
	v_div_scale_f32 v91, vcc, 1.0, v30, 1.0
	v_mul_f32_e32 v93, v91, v89
	v_fma_f32 v102, -v85, v93, v91
	v_fmac_f32_e32 v93, v102, v89
	v_fma_f32 v85, -v85, v93, v91
	v_div_fmas_f32 v85, v85, v89, v93
	v_div_fixup_f32 v30, v85, v30, 1.0
	v_div_scale_f32 v85, s[8:9], v27, v27, 1.0
	v_rcp_f32_e32 v89, v85
	v_pk_mul_f32 v[104:105], v[18:19], v[30:31]
	v_exp_f32_e32 v7, v7
	v_pk_fma_f32 v[0:1], v[12:13], v[138:139], v[0:1]
	v_fma_f32 v91, -v85, v89, 1.0
	v_fmac_f32_e32 v89, v91, v89
	v_div_scale_f32 v91, vcc, 1.0, v27, 1.0
	v_mul_f32_e32 v93, v91, v89
	v_fma_f32 v102, -v85, v93, v91
	v_fmac_f32_e32 v93, v102, v89
	v_fma_f32 v85, -v85, v93, v91
	v_div_fmas_f32 v85, v85, v89, v93
	v_div_fixup_f32 v27, v85, v27, 1.0
	v_div_scale_f32 v85, s[8:9], v26, v26, 1.0
	v_rcp_f32_e32 v89, v85
	v_pk_add_f32 v[6:7], v[6:7], 1.0 op_sel_hi:[1,0]
	v_mul_f32_e32 v4, 0xbfb8aa3b, v0
	v_div_scale_f32 v8, s[8:9], v7, v7, 1.0
	v_fma_f32 v91, -v85, v89, 1.0
	v_fmac_f32_e32 v89, v91, v89
	v_div_scale_f32 v91, vcc, 1.0, v26, 1.0
	v_mul_f32_e32 v93, v91, v89
	v_fma_f32 v102, -v85, v93, v91
	v_fmac_f32_e32 v93, v102, v89
	v_fma_f32 v85, -v85, v93, v91
	v_div_fmas_f32 v85, v85, v89, v93
	v_div_fixup_f32 v26, v85, v26, 1.0
	v_pk_mul_f32 v[102:103], v[16:17], v[26:27]
	flat_load_dwordx4 v[16:19], v[20:21] offset:16
	s_nop 0
	flat_load_dwordx4 v[20:23], v[22:23] offset:16
	s_nop 0
	flat_load_dwordx4 v[24:27], v[24:25] offset:16
	s_nop 0
	flat_load_dwordx4 v[28:31], v[28:29] offset:16
	v_rcp_f32_e32 v9, v8
	v_mul_f32_e32 v5, 0xbfb8aa3b, v1
	v_exp_f32_e32 v4, v4
	v_exp_f32_e32 v5, v5
	v_fma_f32 v10, -v8, v9, 1.0
	v_fmac_f32_e32 v9, v10, v9
	v_pk_mul_f32 v[140:141], v[102:103], v[102:103]
	v_pk_add_f32 v[4:5], v[4:5], 1.0 op_sel_hi:[1,0]
	v_pk_mul_f32 v[122:123], v[104:105], v[104:105]
	s_waitcnt vmcnt(0) lgkmcnt(0)
; __device__ __forceinline__ float bflo(unsigned w) { return __uint_as_float(w << 16); }
; __device__ __forceinline__ float bfhi(unsigned w) { return __uint_as_float(w & 0xffff0000u); }
; __device__ __forceinline__ float sigmoidf_(float x) { return __frcp_rn(1.f + __expf(-x)); }
; __device__ __forceinline__ void prepB(const Params& p, int h, int n, char* shmc, int tid, int wv) {
;     ...
;       float out[2][8];
; #pragma unroll
;       for (int tt = 0; tt < 2; ++tt)
; #pragma unroll
;         for (int i = 0; i < 8; ++i) out[tt][i] = 0.f;
; #pragma unroll
;       for (int rr = 0; rr < 5; ++rr) {
;         const uint4 raw = rawv[rr];
;         const unsigned rw[4] = {raw.x, raw.y, raw.z, raw.w};
;         float xv[8];
; #pragma unroll
;         for (int i = 0; i < 4; ++i) { xv[2 * i] = bflo(rw[i]); xv[2 * i + 1] = bfhi(rw[i]); }
; #pragma unroll
;         for (int tt = 0; tt < 2; ++tt) {
;           const int j = rr - tt;
;           if (j >= 0 && j < 4) {
; #pragma unroll
;             for (int i = 0; i < 8; ++i) out[tt][i] += w[j][i] * xv[i];
;           }
;         }
;       }
; #pragma unroll
;       for (int tt = 0; tt < 2; ++tt) {
;         const int t = t0 + tt;
;         float ss = 0.f;
; #pragma unroll
;         for (int i = 0; i < 8; ++i) { const float o = out[tt][i]; out[tt][i] = o * sigmoidf_(o); ss += out[tt][i] * out[tt][i]; }
	v_pk_fma_f32 v[148:149], v[16:17], v[110:111], 0 op_sel_hi:[1,1,0]
	s_nop 0
	v_pk_fma_f32 v[148:149], v[20:21], v[114:115], v[148:149]
	v_pk_fma_f32 v[146:147], v[18:19], v[112:113], 0 op_sel_hi:[1,1,0]
	v_pk_fma_f32 v[148:149], v[24:25], v[120:121], v[148:149]
	v_pk_fma_f32 v[146:147], v[22:23], v[116:117], v[146:147]
	v_pk_fma_f32 v[142:143], v[28:29], v[142:143], v[148:149]
	v_pk_fma_f32 v[146:147], v[26:27], v[118:119], v[146:147]
	v_mul_f32_e32 v85, 0xbfb8aa3b, v142
	v_pk_fma_f32 v[144:145], v[30:31], v[144:145], v[146:147]
	v_exp_f32_e32 v146, v85
	v_mul_f32_e32 v85, 0xbfb8aa3b, v143
	v_exp_f32_e32 v147, v85
	v_mul_f32_e32 v85, 0xbfb8aa3b, v144
	v_exp_f32_e32 v148, v85
	v_mul_f32_e32 v85, 0xbfb8aa3b, v145
	v_exp_f32_e32 v149, v85
	v_pk_add_f32 v[146:147], v[146:147], 1.0 op_sel_hi:[1,0]
	v_pk_add_f32 v[148:149], v[148:149], 1.0 op_sel_hi:[1,0]
	s_nop 0
	v_div_scale_f32 v85, s[8:9], v149, v149, 1.0
	v_rcp_f32_e32 v89, v85
	s_nop 0
	v_fma_f32 v91, -v85, v89, 1.0
	v_fmac_f32_e32 v89, v91, v89
	v_div_scale_f32 v91, vcc, 1.0, v149, 1.0
	v_mul_f32_e32 v93, v91, v89
	v_fma_f32 v150, -v85, v93, v91
	v_fmac_f32_e32 v93, v150, v89
	v_fma_f32 v85, -v85, v93, v91
	v_div_fmas_f32 v85, v85, v89, v93
	v_div_fixup_f32 v149, v85, v149, 1.0
	v_div_scale_f32 v85, s[8:9], v148, v148, 1.0
	v_rcp_f32_e32 v89, v85
	s_nop 0
	v_fma_f32 v91, -v85, v89, 1.0
	v_fmac_f32_e32 v89, v91, v89
	v_div_scale_f32 v91, vcc, 1.0, v148, 1.0
	v_mul_f32_e32 v93, v91, v89
	v_fma_f32 v150, -v85, v93, v91
	v_fmac_f32_e32 v93, v150, v89
	v_fma_f32 v85, -v85, v93, v91
	v_div_fmas_f32 v85, v85, v89, v93
	v_div_fixup_f32 v148, v85, v148, 1.0
	v_div_scale_f32 v85, s[8:9], v147, v147, 1.0
	v_rcp_f32_e32 v89, v85
	v_pk_mul_f32 v[144:145], v[144:145], v[148:149]
	v_fma_f32 v91, -v85, v89, 1.0
	v_fmac_f32_e32 v89, v91, v89
	v_div_scale_f32 v91, vcc, 1.0, v147, 1.0
	v_mul_f32_e32 v93, v91, v89
	v_fma_f32 v150, -v85, v93, v91
	v_fmac_f32_e32 v93, v150, v89
	v_fma_f32 v85, -v85, v93, v91
	v_div_fmas_f32 v85, v85, v89, v93
	v_div_fixup_f32 v147, v85, v147, 1.0
	v_div_scale_f32 v85, s[8:9], v146, v146, 1.0
	v_rcp_f32_e32 v89, v85
	s_nop 0
	v_fma_f32 v91, -v85, v89, 1.0
	v_fmac_f32_e32 v89, v91, v89
	v_div_scale_f32 v91, vcc, 1.0, v146, 1.0
	v_mul_f32_e32 v93, v91, v89
	v_fma_f32 v150, -v85, v93, v91
	v_fmac_f32_e32 v93, v150, v89
	v_fma_f32 v85, -v85, v93, v91
	v_div_fmas_f32 v85, v85, v89, v93
	v_div_scale_f32 v10, vcc, 1.0, v7, 1.0
	v_mul_f32_e32 v11, v10, v9
	v_fma_f32 v12, -v8, v11, v10
	v_fmac_f32_e32 v11, v12, v9
	v_fma_f32 v8, -v8, v11, v10
	v_div_fmas_f32 v8, v8, v9, v11
	v_div_fixup_f32 v7, v8, v7, 1.0
	v_div_scale_f32 v8, s[8:9], v6, v6, 1.0
	v_rcp_f32_e32 v9, v8
	v_div_fixup_f32 v146, v85, v146, 1.0
	v_pk_mul_f32 v[142:143], v[142:143], v[146:147]
	v_pk_mul_f32 v[146:147], v[144:145], v[144:145]
	v_fma_f32 v10, -v8, v9, 1.0
	v_fmac_f32_e32 v9, v10, v9
	v_div_scale_f32 v10, vcc, 1.0, v6, 1.0
	v_mul_f32_e32 v11, v10, v9
	v_fma_f32 v12, -v8, v11, v10
	v_fmac_f32_e32 v11, v12, v9
	v_fma_f32 v8, -v8, v11, v10
	v_div_fmas_f32 v8, v8, v9, v11
	v_div_fixup_f32 v6, v8, v6, 1.0
	v_div_scale_f32 v8, s[8:9], v5, v5, 1.0
	v_rcp_f32_e32 v9, v8
	v_pk_mul_f32 v[2:3], v[2:3], v[6:7]
	v_pk_mul_f32 v[148:149], v[142:143], v[142:143]
	v_fma_f32 v10, -v8, v9, 1.0
	v_fmac_f32_e32 v9, v10, v9
	v_div_scale_f32 v10, vcc, 1.0, v5, 1.0
	v_mul_f32_e32 v11, v10, v9
	v_fma_f32 v12, -v8, v11, v10
	v_fmac_f32_e32 v11, v12, v9
	v_fma_f32 v8, -v8, v11, v10
	v_div_fmas_f32 v8, v8, v9, v11
	v_div_fixup_f32 v5, v8, v5, 1.0
	v_div_scale_f32 v8, s[8:9], v4, v4, 1.0
	v_rcp_f32_e32 v9, v8
	s_nop 0
	v_fma_f32 v10, -v8, v9, 1.0
	v_fmac_f32_e32 v9, v10, v9
	v_div_scale_f32 v10, vcc, 1.0, v4, 1.0
	v_mul_f32_e32 v11, v10, v9
	v_fma_f32 v12, -v8, v11, v10
	v_fmac_f32_e32 v11, v12, v9
	v_fma_f32 v8, -v8, v11, v10
	v_div_fmas_f32 v8, v8, v9, v11
	v_div_fixup_f32 v4, v8, v4, 1.0
	v_pk_mul_f32 v[0:1], v[0:1], v[4:5]
	v_mov_b32_e32 v8, v140
	v_pk_mul_f32 v[6:7], v[0:1], v[0:1]
	v_pk_fma_f32 v[10:11], v[16:17], v[106:107], 0 op_sel_hi:[1,1,0]
	v_mov_b32_e32 v9, v6
	v_mov_b32_e32 v6, v141
	v_pk_add_f32 v[6:7], v[8:9], v[6:7]
	v_pk_fma_f32 v[8:9], v[18:19], v[108:109], 0 op_sel_hi:[1,1,0]
	v_pk_fma_f32 v[10:11], v[20:21], v[110:111], v[10:11]
	v_pk_fma_f32 v[8:9], v[22:23], v[112:113], v[8:9]
	v_pk_fma_f32 v[10:11], v[24:25], v[114:115], v[10:11]
	v_pk_fma_f32 v[8:9], v[26:27], v[116:117], v[8:9]
	v_pk_fma_f32 v[10:11], v[28:29], v[120:121], v[10:11]
	v_pk_fma_f32 v[8:9], v[30:31], v[118:119], v[8:9]
	v_mul_f32_e32 v12, 0xbfb8aa3b, v10
	v_mul_f32_e32 v14, 0xbfb8aa3b, v8
	v_mul_f32_e32 v15, 0xbfb8aa3b, v9
	v_exp_f32_e32 v14, v14
; __device__ __forceinline__ unsigned pack2(float a, float b) { const f32v2_ v = {a, b}; const bf16v2_ r = __builtin_convertvector(v, bf16v2_); return __builtin_bit_cast(unsigned, r); }
; __device__ __forceinline__ float shfl_idx(float v, int srclane) { return __int_as_float(__builtin_amdgcn_ds_bpermute(srclane << 2, __float_as_int(v))); }
; __device__ __forceinline__ uint4 ldg16(const void* p) { const u32x4 v = *(const __attribute__((address_space(1))) u32x4*)(p); return make_uint4(v.x, v.y, v.z, v.w); }
; __device__ __forceinline__ int perm32(int c) { return ((c >> 2) & 3) * 8 + ((c >> 4) & 1) * 4 + (c & 3); }
; __device__ __forceinline__ float sigmoidf_(float x) { return __frcp_rn(1.f + __expf(-x)); }
; __device__ __forceinline__ void prepB(const Params& p, int h, int n, char* shmc, int tid, int wv) {
;     ...
;       for (int rr = 0; rr < 5; ++rr) {
;         const long tok = rowbase + t0 - 3 + rr;
;         rawv[rr] = make_uint4(0u, 0u, 0u, 0u);
;         if (tok >= 0) rawv[rr] = ldg16(GQKV + tok * 3072 + colg);
;       }
;     ...
;       for (int tt = 0; tt < 2; ++tt) {
;         const int t = t0 + tt;
;         float ss = 0.f;
; #pragma unroll
;         for (int i = 0; i < 8; ++i) { const float o = out[tt][i]; out[tt][i] = o * sigmoidf_(o); ss += out[tt][i] * out[tt][i]; }
;         if (sig < 2) {
; #pragma unroll
;           for (int o = 1; o < 16; o <<= 1) ss += shfl_idx(ss, (tid & 63) ^ o);
;           const float rs = rsqrtf(ss + EPS_);
;           if (sig == 0) {
;             const float eg = __expf(gcS[t]);
;             float qn[8];
; #pragma unroll
;             for (int i = 0; i < 8; ++i) { qn[i] = out[tt][i] * rs * 0.08838834764831845f; qB[t * 136 + c0 + i] = f2bf(qn[i]); }
;             u16* qd = QPB + (long)tix * 8192;
; #pragma unroll
;             for (int g = 0; g < 2; ++g) {
;               uint2 o; o.x = pack2(qn[4 * g] * eg, qn[4 * g + 1] * eg); o.y = pack2(qn[4 * g + 2] * eg, qn[4 * g + 3] * eg);
;               const int p0 = (c0 & ~31) + perm32((c0 & 31) + 4 * g);
;               *(uint2*)(qd + ((((t >> 4) * 4 + (p0 >> 5)) * 64 + ((p0 >> 3) & 3) * 16 + (t & 15)) * 8) + (p0 & 7)) = o;
;             }
;           } else {
; #pragma unroll
;             for (int i = 0; i < 8; ++i) { const float kn = out[tt][i] * rs; kF[t * 128 + c0 + i] = kn; kB[t * 136 + c0 + i] = f2bf(kn); }
	v_exp_f32_e32 v15, v15
	v_mul_f32_e32 v13, 0xbfb8aa3b, v11
	v_exp_f32_e32 v12, v12
	v_exp_f32_e32 v13, v13
	v_pk_add_f32 v[14:15], v[14:15], 1.0 op_sel_hi:[1,0]
	v_pk_mul_f32 v[4:5], v[2:3], v[2:3]
	v_div_scale_f32 v16, s[8:9], v15, v15, 1.0
	v_rcp_f32_e32 v17, v16
	v_pk_add_f32 v[12:13], v[12:13], 1.0 op_sel_hi:[1,0]
	v_or_b32_e32 v22, 0x800, v87
	v_lshlrev_b32_e32 v212, 1, v22
	v_fma_f32 v18, -v16, v17, 1.0
	v_fmac_f32_e32 v17, v18, v17
	v_div_scale_f32 v18, vcc, 1.0, v15, 1.0
	v_mul_f32_e32 v19, v18, v17
	v_fma_f32 v20, -v16, v19, v18
	v_fmac_f32_e32 v19, v20, v17
	v_fma_f32 v16, -v16, v19, v18
	v_div_fmas_f32 v16, v16, v17, v19
	v_div_fixup_f32 v15, v16, v15, 1.0
	v_div_scale_f32 v16, s[8:9], v14, v14, 1.0
	v_rcp_f32_e32 v17, v16
	s_nop 0
	v_fma_f32 v18, -v16, v17, 1.0
	v_fmac_f32_e32 v17, v18, v17
	v_div_scale_f32 v18, vcc, 1.0, v14, 1.0
	v_mul_f32_e32 v19, v18, v17
	v_fma_f32 v20, -v16, v19, v18
	v_fmac_f32_e32 v19, v20, v17
	v_fma_f32 v16, -v16, v19, v18
	v_div_fmas_f32 v16, v16, v17, v19
	v_div_fixup_f32 v14, v16, v14, 1.0
	v_div_scale_f32 v16, s[8:9], v13, v13, 1.0
	v_rcp_f32_e32 v17, v16
	v_pk_mul_f32 v[8:9], v[8:9], v[14:15]
	v_fma_f32 v18, -v16, v17, 1.0
	v_fmac_f32_e32 v17, v18, v17
	v_div_scale_f32 v18, vcc, 1.0, v13, 1.0
	v_mul_f32_e32 v19, v18, v17
	v_fma_f32 v20, -v16, v19, v18
	v_fmac_f32_e32 v19, v20, v17
	v_fma_f32 v16, -v16, v19, v18
	v_div_fmas_f32 v16, v16, v17, v19
	v_div_fixup_f32 v13, v16, v13, 1.0
	v_div_scale_f32 v16, s[8:9], v12, v12, 1.0
	v_rcp_f32_e32 v17, v16
	s_mov_b32 s8, 0x358637bd
	v_fma_f32 v18, -v16, v17, 1.0
	v_fmac_f32_e32 v17, v18, v17
	v_div_scale_f32 v18, vcc, 1.0, v12, 1.0
	v_mul_f32_e32 v19, v18, v17
	v_fma_f32 v20, -v16, v19, v18
	v_fmac_f32_e32 v19, v20, v17
	v_fma_f32 v16, -v16, v19, v18
	v_div_fmas_f32 v16, v16, v17, v19
	v_div_fixup_f32 v12, v16, v12, 1.0
	v_pk_mul_f32 v[10:11], v[10:11], v[12:13]
	v_mov_b32_e32 v16, v122
	v_mov_b32_e32 v17, v4
	v_pk_mul_f32 v[14:15], v[10:11], v[10:11]
	v_pk_add_f32 v[6:7], v[6:7], v[16:17]
	v_mov_b32_e32 v4, v123
	v_pk_add_f32 v[4:5], v[6:7], v[4:5]
	v_mov_b32_e32 v6, v148
	v_mov_b32_e32 v7, v14
	v_pk_mul_f32 v[12:13], v[8:9], v[8:9]
	v_pk_add_f32 v[4:5], v[4:5], v[6:7]
	v_mov_b32_e32 v14, v149
	v_pk_add_f32 v[4:5], v[4:5], v[14:15]
	v_mov_b32_e32 v6, v146
	v_mov_b32_e32 v7, v12
	v_pk_add_f32 v[4:5], v[4:5], v[6:7]
	v_mov_b32_e32 v12, v147
	v_pk_add_f32 v[4:5], v[4:5], v[12:13]
	ds_bpermute_b32 v7, v157, v5
	ds_bpermute_b32 v6, v157, v4
	v_lshl_add_u64 v[20:21], v[36:37], 0, v[212:213]
	s_waitcnt lgkmcnt(0)
	v_pk_add_f32 v[4:5], v[4:5], v[6:7]
	ds_bpermute_b32 v7, v158, v5
	ds_bpermute_b32 v6, v158, v4
	s_waitcnt lgkmcnt(0)
	v_pk_add_f32 v[4:5], v[4:5], v[6:7]
	ds_bpermute_b32 v7, v159, v5
	ds_bpermute_b32 v6, v159, v4
	s_waitcnt lgkmcnt(0)
	v_pk_add_f32 v[4:5], v[4:5], v[6:7]
	ds_bpermute_b32 v7, v160, v5
	ds_bpermute_b32 v6, v160, v4
	s_waitcnt lgkmcnt(0)
	v_pk_add_f32 v[4:5], v[4:5], v[6:7]
	s_nop 0
	v_pk_add_f32 v[12:13], v[4:5], s[8:9] op_sel_hi:[1,0]
	s_nop 0
	v_mul_f32_e32 v4, 0x4b800000, v13
	v_cmp_gt_f32_e64 s[86:87], s70, v13
	v_cmp_gt_f32_e32 vcc, s70, v12
	s_nop 0
	v_cndmask_b32_e64 v4, v13, v4, s[86:87]
	v_rsq_f32_e32 v4, v4
	v_add_u32_e32 v13, v73, v162
	v_mul_f32_e32 v5, 0x45800000, v4
	v_cndmask_b32_e64 v6, v4, v5, s[86:87]
	v_pk_mul_f32 v[0:1], v[0:1], v[6:7] op_sel_hi:[1,0]
	v_pk_mul_f32 v[2:3], v[2:3], v[6:7] op_sel_hi:[1,0]
	v_pk_mul_f32 v[4:5], v[10:11], v[6:7] op_sel_hi:[1,0]
	v_pk_mul_f32 v[6:7], v[8:9], v[6:7] op_sel_hi:[1,0]
	ds_write_b128 v240, v[0:3]
	ds_write_b128 v240, v[4:7] offset:16
	v_cvt_pk_bf16_f32 v7, v6, v7
	v_cvt_pk_bf16_f32 v6, v4, v5
	v_cvt_pk_bf16_f32 v4, v0, v1
	v_mul_f32_e32 v0, 0x4b800000, v12
	v_cndmask_b32_e32 v0, v12, v0, vcc
	v_rsq_f32_e32 v0, v0
	v_cvt_pk_bf16_f32 v5, v2, v3
	ds_write_b128 v13, v[4:7]
	v_add_u32_e32 v8, v73, v164
	v_mul_f32_e32 v1, 0x45800000, v0
	v_cndmask_b32_e32 v6, v0, v1, vcc
	v_pk_mul_f32 v[0:1], v[102:103], v[6:7] op_sel_hi:[1,0]
	v_pk_mul_f32 v[2:3], v[104:105], v[6:7] op_sel_hi:[1,0]
	v_pk_mul_f32 v[4:5], v[142:143], v[6:7] op_sel_hi:[1,0]
	v_pk_mul_f32 v[6:7], v[144:145], v[6:7] op_sel_hi:[1,0]
	ds_write_b128 v241, v[4:7] offset:16
	v_cvt_pk_bf16_f32 v7, v6, v7
	v_cvt_pk_bf16_f32 v6, v4, v5
	v_cvt_pk_bf16_f32 v5, v2, v3
	v_cvt_pk_bf16_f32 v4, v0, v1
	ds_write_b128 v241, v[0:3]
	ds_write_b128 v8, v[4:7]
	v_mov_b32_e32 v3, 0
	v_mov_b32_e32 v7, 0
	v_mov_b32_e32 v6, 0
	v_mov_b32_e32 v5, 0
	v_mov_b32_e32 v4, 0
	s_and_saveexec_b64 s[86:87], s[76:77]
	s_cbranch_execz .LBB0_458
	v_mad_u64_u32 v[0:1], s[8:9], v34, s42, v[20:21]
	v_mad_i32_i24 v1, v35, s42, v1
	global_load_dwordx4 v[4:7], v[0:1], off
